# MLA: 4-slot ring; waves 4-7 publish in front of and meet the barrier behind the 3rd QK MFMA
# baseline (speedup 1.0000x reference)
; __device__ __forceinline__ void finishSM9(f32x16& p0, f32x16& p1, float alpha, float& l_reg, v8i32& p8) {
; #pragma unroll
;   for (int r = 0; r < 16; ++r) { p0[r] = __builtin_amdgcn_exp2f(p0[r]); p1[r] = __builtin_amdgcn_exp2f(p1[r]); }
;   float ps = 0;
; #pragma unroll
;   for (int r = 0; r < 16; ++r) ps += p0[r];
; #pragma unroll
;   for (int r = 0; r < 16; ++r) ps += p1[r];
;   { auto rr = __builtin_amdgcn_permlane32_swap(__float_as_uint(ps), __float_as_uint(ps), false, false);
;     ps = __uint_as_float(rr[0]) + __uint_as_float(rr[1]); }
;   l_reg = l_reg * alpha + ps;
; #pragma unroll
;   for (int g = 0; g < 4; ++g) {
;     int w = __builtin_amdgcn_cvt_pk_fp8_f32(p0[4 * g], p0[4 * g + 1], 0, false); p8[g] = __builtin_amdgcn_cvt_pk_fp8_f32(p0[4 * g + 2], p0[4 * g + 3], w, true);
;     int u = __builtin_amdgcn_cvt_pk_fp8_f32(p1[4 * g], p1[4 * g + 1], 0, false); p8[4 + g] = __builtin_amdgcn_cvt_pk_fp8_f32(p1[4 * g + 2], p1[4 * g + 3], u, true); }
; }
; __device__ __forceinline__ void pv8(f32x16* o, const char* Vt, const v8i32 p8, int r32, int hi) {
;   const int sw = (r32 >> 2) & 3, a0 = r32 * 64 + (((hi * 2) ^ sw) << 4), a1 = r32 * 64 + (((hi * 2 + 1) ^ sw) << 4);
; #pragma unroll
;   for (int d0 = 0; d0 < 4; ++d0) {
;     const v8i32 vf = cat8(*reinterpret_cast<const v4i32*>(Vt + d0 * 2048 + a0), *reinterpret_cast<const v4i32*>(Vt + d0 * 2048 + a1));
;     o[d0] = __builtin_amdgcn_mfma_scale_f32_32x32x64_f8f6f4(p8, vf, o[d0], 0, 0, 0, 127, 0, 127); }
; }
; __device__ __forceinline__ void qkt9(f32x16& p0, f32x16& p1, const char* Kn, const char* Kr, const v8i32* qf, const float init, int r32, int hi) {
; #pragma unroll
;   for (int r = 0; r < 16; ++r) { p0[r] = init; p1[r] = init; }
; #pragma unroll
;   for (int s = 0; s < 2; ++s) { const int c0 = s * 4 + hi * 2;
;     const v8i32 a0 = cat8(*reinterpret_cast<const v4i32*>(Kn + KN8SW(r32, c0)), *reinterpret_cast<const v4i32*>(Kn + KN8SW(r32, c0 + 1)));
;     const v8i32 a1 = cat8(*reinterpret_cast<const v4i32*>(Kn + 4096 + KN8SW(r32, c0)), *reinterpret_cast<const v4i32*>(Kn + 4096 + KN8SW(r32, c0 + 1)));
;     p0 = __builtin_amdgcn_mfma_scale_f32_32x32x64_f8f6f4(a0, qf[s], p0, 0, 0, 0, 127, 0, 124);
;     p1 = __builtin_amdgcn_mfma_scale_f32_32x32x64_f8f6f4(a1, qf[s], p1, 0, 0, 0, 127, 0, 124); }
;   { const int c0 = hi * 2;
.LBB0_1321:
	global_load_dwordx4 v[158:161], v176, s[18:19]
	global_load_dwordx4 v[162:165], v178, s[16:17]
	global_load_dwordx4 v[154:157], v[180:181], off
	ds_read_b128 v[114:117], v215 offset:24576
	ds_read_b128 v[118:121], v216 offset:24576
	ds_read_b128 v[222:225], v215 offset:28672
	ds_read_b128 v[226:229], v216 offset:28672
	v_add_u32_e32 v176, 0x2000, v176
	v_add_u32_e32 v178, 0x20000, v178
	s_mov_b64 s[20:21], 0x1000
	v_lshl_add_u64 v[180:181], v[180:181], 0, s[20:21]
	v_exp_f32_e32 v0, v82
	v_exp_f32_e32 v177, v83
	v_exp_f32_e32 v179, v84
	v_exp_f32_e32 v254, v85
	v_add_f32_e32 v219, v0, v177
	v_cvt_pk_fp8_f32 v246, v0, v177
	v_add_f32_e32 v219, v179, v219
	v_add_f32_e32 v219, v254, v219
	v_cvt_pk_fp8_f32 v246, v179, v254 op_sel:[0,0,1]
	s_waitcnt lgkmcnt(2)
	v_mfma_scale_f32_32x32x64_f8f6f4 v[114:129], v[114:121], v[146:153], v[230:245], v194, v193 op_sel_hi:[0,0,0]
	v_exp_f32_e32 v0, v86
	v_exp_f32_e32 v177, v87
	v_exp_f32_e32 v179, v88
	v_exp_f32_e32 v254, v89
	v_add_f32_e32 v219, v0, v219
	v_add_f32_e32 v219, v177, v219
	v_cvt_pk_fp8_f32 v247, v0, v177
	v_add_f32_e32 v219, v179, v219
	v_add_f32_e32 v219, v254, v219
	v_cvt_pk_fp8_f32 v247, v179, v254 op_sel:[0,0,1]
	ds_read_b128 v[82:85], v213 offset:24576
	ds_read_b128 v[86:89], v214 offset:24576
	s_waitcnt lgkmcnt(2)
	v_mfma_scale_f32_32x32x64_f8f6f4 v[98:113], v[222:229], v[146:153], v[230:245], v194, v193 op_sel_hi:[0,0,0]
	ds_read_b128 v[222:225], v213 offset:28672
	ds_read_b128 v[226:229], v214 offset:28672
	v_exp_f32_e32 v0, v90
	v_exp_f32_e32 v177, v91
	v_exp_f32_e32 v179, v92
	v_exp_f32_e32 v254, v93
	v_add_f32_e32 v219, v0, v219
	v_add_f32_e32 v219, v177, v219
	v_cvt_pk_fp8_f32 v248, v0, v177
	v_add_f32_e32 v219, v179, v219
	v_add_f32_e32 v219, v254, v219
	v_cvt_pk_fp8_f32 v248, v179, v254 op_sel:[0,0,1]
	v_exp_f32_e32 v0, v94
	v_exp_f32_e32 v177, v95
	v_exp_f32_e32 v179, v96
	v_exp_f32_e32 v254, v97
	v_add_f32_e32 v219, v0, v219
	v_add_f32_e32 v219, v177, v219
	v_cvt_pk_fp8_f32 v249, v0, v177
	v_add_f32_e32 v219, v179, v219
	v_add_f32_e32 v219, v254, v219
	v_cvt_pk_fp8_f32 v249, v179, v254 op_sel:[0,0,1]
	ds_read_b128 v[90:93], v185 offset:36864
	ds_read_b128 v[94:97], v186 offset:36864
	s_waitcnt lgkmcnt(4)
	v_mfma_scale_f32_32x32x64_f8f6f4 v[114:129], v[82:89], v[138:145], v[114:129], v194, v193 op_sel_hi:[0,0,0]
	v_exp_f32_e32 v0, v66
	v_exp_f32_e32 v177, v67
	v_exp_f32_e32 v179, v68
	v_exp_f32_e32 v254, v69
	v_add_f32_e32 v219, v0, v219
	v_add_f32_e32 v219, v177, v219
	v_cvt_pk_fp8_f32 v250, v0, v177
	v_add_f32_e32 v219, v179, v219
	v_add_f32_e32 v219, v254, v219
	v_cvt_pk_fp8_f32 v250, v179, v254 op_sel:[0,0,1]
	s_waitcnt lgkmcnt(2)
	v_mfma_scale_f32_32x32x64_f8f6f4 v[98:113], v[222:229], v[138:145], v[98:113], v194, v193 op_sel_hi:[0,0,0]
	ds_read_b128 v[222:225], v185 offset:38912
	ds_read_b128 v[226:229], v186 offset:38912
	v_exp_f32_e32 v0, v70
	v_exp_f32_e32 v177, v71
	v_exp_f32_e32 v179, v72
	v_exp_f32_e32 v254, v73
	v_add_f32_e32 v219, v0, v219
	v_add_f32_e32 v219, v177, v219
	v_cvt_pk_fp8_f32 v251, v0, v177
	v_add_f32_e32 v219, v179, v219
	v_add_f32_e32 v219, v254, v219
	v_cvt_pk_fp8_f32 v251, v179, v254 op_sel:[0,0,1]
	v_exp_f32_e32 v0, v74
	v_exp_f32_e32 v177, v75
	v_exp_f32_e32 v179, v76
	v_exp_f32_e32 v254, v77
	v_add_f32_e32 v219, v0, v219
	v_add_f32_e32 v219, v177, v219
	v_cvt_pk_fp8_f32 v252, v0, v177
	v_add_f32_e32 v219, v179, v219
	v_add_f32_e32 v219, v254, v219
	v_cvt_pk_fp8_f32 v252, v179, v254 op_sel:[0,0,1]
	s_waitcnt lgkmcnt(2)
	v_mfma_scale_f32_32x32x64_f8f6f4 v[114:129], v[90:97], v[130:137], v[114:129], v194, v193 op_sel_hi:[0,0,0]
	v_exp_f32_e32 v0, v78
	v_exp_f32_e32 v177, v79
	v_exp_f32_e32 v179, v80
	v_exp_f32_e32 v254, v81
	v_add_f32_e32 v219, v0, v219
	v_add_f32_e32 v219, v177, v219
	v_cvt_pk_fp8_f32 v253, v0, v177
	v_add_f32_e32 v219, v179, v219
	v_add_f32_e32 v219, v254, v219
	v_cvt_pk_fp8_f32 v253, v179, v254 op_sel:[0,0,1]
	ds_read_b128 v[90:93], v185 offset:0
	ds_read_b128 v[94:97], v186 offset:0
	ds_read_b128 v[82:85], v185 offset:2048
	ds_read_b128 v[86:89], v186 offset:2048
	ds_read_b128 v[74:77], v185 offset:4096
	ds_read_b128 v[78:81], v186 offset:4096
	ds_read_b128 v[66:69], v185 offset:6144
	ds_read_b128 v[70:73], v186 offset:6144
	s_waitcnt lgkmcnt(8)
	v_mfma_scale_f32_32x32x64_f8f6f4 v[98:113], v[222:229], v[130:137], v[98:113], v194, v193 op_sel_hi:[0,0,0]
	v_mov_b32_e32 v0, v219
	s_nop 1
	v_permlane32_swap_b32_e32 v219, v0
	v_add_f32_e32 v219, v219, v0
	v_fma_f32 v209, v209, v218, v219
	v_max_f32_e32 v177, v114, v115
	v_max3_f32 v177, v177, v116, v117
	v_max3_f32 v177, v177, v118, v119
	v_max3_f32 v177, v177, v120, v121
	v_max3_f32 v177, v177, v122, v123
	v_max3_f32 v177, v177, v124, v125
	v_max3_f32 v177, v177, v126, v127
	v_max3_f32 v177, v177, v128, v129
	s_waitcnt lgkmcnt(6)
	v_mfma_scale_f32_32x32x64_f8f6f4 v[50:65], v[246:253], v[90:97], v[50:65], v194, v194 op_sel_hi:[0,0,0]
	s_waitcnt lgkmcnt(4)
	v_mfma_scale_f32_32x32x64_f8f6f4 v[34:49], v[246:253], v[82:89], v[34:49], v194, v194 op_sel_hi:[0,0,0]
	s_waitcnt lgkmcnt(2)
	v_mfma_scale_f32_32x32x64_f8f6f4 v[18:33], v[246:253], v[74:81], v[18:33], v194, v194 op_sel_hi:[0,0,0]
	s_waitcnt vmcnt(0)
	ds_write_b128 v172, v[158:161]
	ds_write_b128 v173, v[162:165] offset:16384
	ds_write_b128 v220, v[154:157] offset:32768
	s_waitcnt lgkmcnt(3)
	v_mfma_scale_f32_32x32x64_f8f6f4 v[2:17], v[246:253], v[66:73], v[2:17], v194, v194 op_sel_hi:[0,0,0]
	s_waitcnt lgkmcnt(0)
	s_barrier
	v_max_f32_e32 v0, v98, v99
	v_max3_f32 v0, v0, v100, v101
	v_max3_f32 v0, v0, v102, v103
	v_max3_f32 v0, v0, v104, v105
	v_max3_f32 v0, v0, v106, v107
	v_max3_f32 v0, v0, v108, v109
	v_max3_f32 v0, v0, v110, v111
	v_max3_f32 v0, v0, v112, v113
	v_max_f32_e32 v177, v177, v0
	v_mov_b32_e32 v0, v177
	v_mov_b32_e32 v221, 1.0
	s_nop 0
	v_permlane32_swap_b32_e32 v177, v0
	v_max_f32_e32 v177, v177, v0
	v_cmp_ge_f32_e32 vcc, s90, v177
	s_cmp_eq_u64 vcc, exec
	s_cbranch_scc0 .Lmla_h0_newmax
; __device__ __forceinline__ void finishSM9(f32x16& p0, f32x16& p1, float alpha, float& l_reg, v8i32& p8) {
; #pragma unroll
;   for (int r = 0; r < 16; ++r) { p0[r] = __builtin_amdgcn_exp2f(p0[r]); p1[r] = __builtin_amdgcn_exp2f(p1[r]); }
;   float ps = 0;
; #pragma unroll
;   for (int r = 0; r < 16; ++r) ps += p0[r];
; #pragma unroll
;   for (int r = 0; r < 16; ++r) ps += p1[r];
;   { auto rr = __builtin_amdgcn_permlane32_swap(__float_as_uint(ps), __float_as_uint(ps), false, false);
;     ps = __uint_as_float(rr[0]) + __uint_as_float(rr[1]); }
;   l_reg = l_reg * alpha + ps;
; #pragma unroll
;   for (int g = 0; g < 4; ++g) {
;     int w = __builtin_amdgcn_cvt_pk_fp8_f32(p0[4 * g], p0[4 * g + 1], 0, false); p8[g] = __builtin_amdgcn_cvt_pk_fp8_f32(p0[4 * g + 2], p0[4 * g + 3], w, true);
;     int u = __builtin_amdgcn_cvt_pk_fp8_f32(p1[4 * g], p1[4 * g + 1], 0, false); p8[4 + g] = __builtin_amdgcn_cvt_pk_fp8_f32(p1[4 * g + 2], p1[4 * g + 3], u, true); }
; }
; __device__ __forceinline__ void pv8(f32x16* o, const char* Vt, const v8i32 p8, int r32, int hi) {
;   const int sw = (r32 >> 2) & 3, a0 = r32 * 64 + (((hi * 2) ^ sw) << 4), a1 = r32 * 64 + (((hi * 2 + 1) ^ sw) << 4);
; #pragma unroll
;   for (int d0 = 0; d0 < 4; ++d0) {
;     const v8i32 vf = cat8(*reinterpret_cast<const v4i32*>(Vt + d0 * 2048 + a0), *reinterpret_cast<const v4i32*>(Vt + d0 * 2048 + a1));
;     o[d0] = __builtin_amdgcn_mfma_scale_f32_32x32x64_f8f6f4(p8, vf, o[d0], 0, 0, 0, 127, 0, 127); }
; }
; __device__ __forceinline__ void qkt9(f32x16& p0, f32x16& p1, const char* Kn, const char* Kr, const v8i32* qf, const float init, int r32, int hi) {
; #pragma unroll
;   for (int r = 0; r < 16; ++r) { p0[r] = init; p1[r] = init; }
; #pragma unroll
;   for (int s = 0; s < 2; ++s) { const int c0 = s * 4 + hi * 2;
;     const v8i32 a0 = cat8(*reinterpret_cast<const v4i32*>(Kn + KN8SW(r32, c0)), *reinterpret_cast<const v4i32*>(Kn + KN8SW(r32, c0 + 1)));
;     const v8i32 a1 = cat8(*reinterpret_cast<const v4i32*>(Kn + 4096 + KN8SW(r32, c0)), *reinterpret_cast<const v4i32*>(Kn + 4096 + KN8SW(r32, c0 + 1)));
;     p0 = __builtin_amdgcn_mfma_scale_f32_32x32x64_f8f6f4(a0, qf[s], p0, 0, 0, 0, 127, 0, 124);
;     p1 = __builtin_amdgcn_mfma_scale_f32_32x32x64_f8f6f4(a1, qf[s], p1, 0, 0, 0, 127, 0, 124); }
;   { const int c0 = hi * 2;
.Lmla_h0_cont:
	global_load_dwordx4 v[158:161], v176, s[18:19]
	global_load_dwordx4 v[162:165], v178, s[16:17]
	global_load_dwordx4 v[154:157], v[180:181], off
	ds_read_b128 v[82:85], v166 offset:16384
	ds_read_b128 v[86:89], v167 offset:16384
	ds_read_b128 v[222:225], v166 offset:20480
	ds_read_b128 v[226:229], v167 offset:20480
	v_add_u32_e32 v176, 0x2000, v176
	v_add_u32_e32 v178, 0x20000, v178
	s_mov_b64 s[20:21], 0x1000
	v_lshl_add_u64 v[180:181], v[180:181], 0, s[20:21]
	v_exp_f32_e32 v0, v114
	v_exp_f32_e32 v177, v115
	v_exp_f32_e32 v179, v116
	v_exp_f32_e32 v254, v117
	v_add_f32_e32 v219, v0, v177
	v_cvt_pk_fp8_f32 v246, v0, v177
	v_add_f32_e32 v219, v179, v219
	v_add_f32_e32 v219, v254, v219
	v_cvt_pk_fp8_f32 v246, v179, v254 op_sel:[0,0,1]
	s_waitcnt lgkmcnt(2)
	v_mfma_scale_f32_32x32x64_f8f6f4 v[82:97], v[82:89], v[146:153], v[230:245], v194, v193 op_sel_hi:[0,0,0]
	v_exp_f32_e32 v0, v118
	v_exp_f32_e32 v177, v119
	v_exp_f32_e32 v179, v120
	v_exp_f32_e32 v254, v121
	v_add_f32_e32 v219, v0, v219
	v_add_f32_e32 v219, v177, v219
	v_cvt_pk_fp8_f32 v247, v0, v177
	v_add_f32_e32 v219, v179, v219
	v_add_f32_e32 v219, v254, v219
	v_cvt_pk_fp8_f32 v247, v179, v254 op_sel:[0,0,1]
	ds_read_b128 v[114:117], v168 offset:16384
	ds_read_b128 v[118:121], v169 offset:16384
	s_waitcnt lgkmcnt(2)
	v_mfma_scale_f32_32x32x64_f8f6f4 v[66:81], v[222:229], v[146:153], v[230:245], v194, v193 op_sel_hi:[0,0,0]
	ds_read_b128 v[222:225], v168 offset:20480
	ds_read_b128 v[226:229], v169 offset:20480
	v_exp_f32_e32 v0, v122
	v_exp_f32_e32 v177, v123
	v_exp_f32_e32 v179, v124
	v_exp_f32_e32 v254, v125
	v_add_f32_e32 v219, v0, v219
	v_add_f32_e32 v219, v177, v219
	v_cvt_pk_fp8_f32 v248, v0, v177
	v_add_f32_e32 v219, v179, v219
	v_add_f32_e32 v219, v254, v219
	v_cvt_pk_fp8_f32 v248, v179, v254 op_sel:[0,0,1]
	v_exp_f32_e32 v0, v126
	v_exp_f32_e32 v177, v127
	v_exp_f32_e32 v179, v128
	v_exp_f32_e32 v254, v129
	v_add_f32_e32 v219, v0, v219
	v_add_f32_e32 v219, v177, v219
	v_cvt_pk_fp8_f32 v249, v0, v177
	v_add_f32_e32 v219, v179, v219
	v_add_f32_e32 v219, v254, v219
	v_cvt_pk_fp8_f32 v249, v179, v254 op_sel:[0,0,1]
	ds_read_b128 v[122:125], v170 offset:32768
	ds_read_b128 v[126:129], v171 offset:32768
	s_waitcnt lgkmcnt(4)
	v_mfma_scale_f32_32x32x64_f8f6f4 v[82:97], v[114:121], v[138:145], v[82:97], v194, v193 op_sel_hi:[0,0,0]
	v_exp_f32_e32 v0, v98
	v_exp_f32_e32 v177, v99
	v_exp_f32_e32 v179, v100
	v_exp_f32_e32 v254, v101
	v_add_f32_e32 v219, v0, v219
	v_add_f32_e32 v219, v177, v219
	v_cvt_pk_fp8_f32 v250, v0, v177
	v_add_f32_e32 v219, v179, v219
	v_add_f32_e32 v219, v254, v219
	v_cvt_pk_fp8_f32 v250, v179, v254 op_sel:[0,0,1]
	s_waitcnt lgkmcnt(2)
	v_mfma_scale_f32_32x32x64_f8f6f4 v[66:81], v[222:229], v[138:145], v[66:81], v194, v193 op_sel_hi:[0,0,0]
	ds_read_b128 v[222:225], v170 offset:34816
	ds_read_b128 v[226:229], v171 offset:34816
	v_exp_f32_e32 v0, v102
	v_exp_f32_e32 v177, v103
	v_exp_f32_e32 v179, v104
	v_exp_f32_e32 v254, v105
	v_add_f32_e32 v219, v0, v219
	v_add_f32_e32 v219, v177, v219
	v_cvt_pk_fp8_f32 v251, v0, v177
	v_add_f32_e32 v219, v179, v219
	v_add_f32_e32 v219, v254, v219
	v_cvt_pk_fp8_f32 v251, v179, v254 op_sel:[0,0,1]
	v_exp_f32_e32 v0, v106
	v_exp_f32_e32 v177, v107
	v_exp_f32_e32 v179, v108
	v_exp_f32_e32 v254, v109
	v_add_f32_e32 v219, v0, v219
	v_add_f32_e32 v219, v177, v219
	v_cvt_pk_fp8_f32 v252, v0, v177
	v_add_f32_e32 v219, v179, v219
	v_add_f32_e32 v219, v254, v219
	v_cvt_pk_fp8_f32 v252, v179, v254 op_sel:[0,0,1]
	s_waitcnt lgkmcnt(2)
	v_mfma_scale_f32_32x32x64_f8f6f4 v[82:97], v[122:129], v[130:137], v[82:97], v194, v193 op_sel_hi:[0,0,0]
	v_exp_f32_e32 v0, v110
	v_exp_f32_e32 v177, v111
	v_exp_f32_e32 v179, v112
	v_exp_f32_e32 v254, v113
	v_add_f32_e32 v219, v0, v219
	v_add_f32_e32 v219, v177, v219
	v_cvt_pk_fp8_f32 v253, v0, v177
	v_add_f32_e32 v219, v179, v219
	v_add_f32_e32 v219, v254, v219
	v_cvt_pk_fp8_f32 v253, v179, v254 op_sel:[0,0,1]
	ds_read_b128 v[122:125], v185 offset:8192
	ds_read_b128 v[126:129], v186 offset:8192
	ds_read_b128 v[114:117], v185 offset:10240
	ds_read_b128 v[118:121], v186 offset:10240
	ds_read_b128 v[106:109], v185 offset:12288
	ds_read_b128 v[110:113], v186 offset:12288
	ds_read_b128 v[98:101], v185 offset:14336
	ds_read_b128 v[102:105], v186 offset:14336
	s_waitcnt lgkmcnt(8)
	v_mfma_scale_f32_32x32x64_f8f6f4 v[66:81], v[222:229], v[130:137], v[66:81], v194, v193 op_sel_hi:[0,0,0]
	v_mov_b32_e32 v0, v219
	s_nop 1
	v_permlane32_swap_b32_e32 v219, v0
	v_add_f32_e32 v219, v219, v0
	v_fma_f32 v209, v209, v221, v219
	v_max_f32_e32 v177, v82, v83
	v_max3_f32 v177, v177, v84, v85
	v_max3_f32 v177, v177, v86, v87
	v_max3_f32 v177, v177, v88, v89
	v_max3_f32 v177, v177, v90, v91
	v_max3_f32 v177, v177, v92, v93
	v_max3_f32 v177, v177, v94, v95
	v_max3_f32 v177, v177, v96, v97
	s_waitcnt lgkmcnt(6)
	v_mfma_scale_f32_32x32x64_f8f6f4 v[50:65], v[246:253], v[122:129], v[50:65], v194, v194 op_sel_hi:[0,0,0]
	s_waitcnt lgkmcnt(4)
	v_mfma_scale_f32_32x32x64_f8f6f4 v[34:49], v[246:253], v[114:121], v[34:49], v194, v194 op_sel_hi:[0,0,0]
	s_waitcnt lgkmcnt(2)
	v_mfma_scale_f32_32x32x64_f8f6f4 v[18:33], v[246:253], v[106:113], v[18:33], v194, v194 op_sel_hi:[0,0,0]
	s_waitcnt vmcnt(0)
	ds_write_b128 v172, v[158:161] offset:8192
	ds_write_b128 v173, v[162:165] offset:24576
	ds_write_b128 v220, v[154:157] offset:36864
	s_waitcnt lgkmcnt(3)
	v_mfma_scale_f32_32x32x64_f8f6f4 v[2:17], v[246:253], v[98:105], v[2:17], v194, v194 op_sel_hi:[0,0,0]
	s_waitcnt lgkmcnt(0)
	s_barrier
	v_max_f32_e32 v0, v66, v67
	v_max3_f32 v0, v0, v68, v69
	v_max3_f32 v0, v0, v70, v71
	v_max3_f32 v0, v0, v72, v73
	v_max3_f32 v0, v0, v74, v75
	v_max3_f32 v0, v0, v76, v77
	v_max3_f32 v0, v0, v78, v79
	v_max3_f32 v0, v0, v80, v81
	v_max_f32_e32 v177, v177, v0
	v_mov_b32_e32 v0, v177
	v_mov_b32_e32 v218, 1.0
	s_nop 0
	v_permlane32_swap_b32_e32 v177, v0
	v_max_f32_e32 v177, v177, v0
	v_cmp_ge_f32_e32 vcc, s90, v177
	s_cmp_eq_u64 vcc, exec
	s_cbranch_scc0 .Lmla_h1_newmax
; __device__ __forceinline__ void finishSM9(f32x16& p0, f32x16& p1, float alpha, float& l_reg, v8i32& p8) {
; #pragma unroll
;   for (int r = 0; r < 16; ++r) { p0[r] = __builtin_amdgcn_exp2f(p0[r]); p1[r] = __builtin_amdgcn_exp2f(p1[r]); }
;   float ps = 0;
; #pragma unroll
;   for (int r = 0; r < 16; ++r) ps += p0[r];
; #pragma unroll
;   for (int r = 0; r < 16; ++r) ps += p1[r];
;   { auto rr = __builtin_amdgcn_permlane32_swap(__float_as_uint(ps), __float_as_uint(ps), false, false);
;     ps = __uint_as_float(rr[0]) + __uint_as_float(rr[1]); }
;   l_reg = l_reg * alpha + ps;
; #pragma unroll
;   for (int g = 0; g < 4; ++g) {
;     int w = __builtin_amdgcn_cvt_pk_fp8_f32(p0[4 * g], p0[4 * g + 1], 0, false); p8[g] = __builtin_amdgcn_cvt_pk_fp8_f32(p0[4 * g + 2], p0[4 * g + 3], w, true);
;     int u = __builtin_amdgcn_cvt_pk_fp8_f32(p1[4 * g], p1[4 * g + 1], 0, false); p8[4 + g] = __builtin_amdgcn_cvt_pk_fp8_f32(p1[4 * g + 2], p1[4 * g + 3], u, true); }
; }
; __device__ __forceinline__ void pv8(f32x16* o, const char* Vt, const v8i32 p8, int r32, int hi) {
;   const int sw = (r32 >> 2) & 3, a0 = r32 * 64 + (((hi * 2) ^ sw) << 4), a1 = r32 * 64 + (((hi * 2 + 1) ^ sw) << 4);
; #pragma unroll
;   for (int d0 = 0; d0 < 4; ++d0) {
;     const v8i32 vf = cat8(*reinterpret_cast<const v4i32*>(Vt + d0 * 2048 + a0), *reinterpret_cast<const v4i32*>(Vt + d0 * 2048 + a1));
;     o[d0] = __builtin_amdgcn_mfma_scale_f32_32x32x64_f8f6f4(p8, vf, o[d0], 0, 0, 0, 127, 0, 127); }
; }
; __device__ __forceinline__ void qkt9(f32x16& p0, f32x16& p1, const char* Kn, const char* Kr, const v8i32* qf, const float init, int r32, int hi) {
; #pragma unroll
;   for (int r = 0; r < 16; ++r) { p0[r] = init; p1[r] = init; }
; #pragma unroll
;   for (int s = 0; s < 2; ++s) { const int c0 = s * 4 + hi * 2;
;     const v8i32 a0 = cat8(*reinterpret_cast<const v4i32*>(Kn + KN8SW(r32, c0)), *reinterpret_cast<const v4i32*>(Kn + KN8SW(r32, c0 + 1)));
;     const v8i32 a1 = cat8(*reinterpret_cast<const v4i32*>(Kn + 4096 + KN8SW(r32, c0)), *reinterpret_cast<const v4i32*>(Kn + 4096 + KN8SW(r32, c0 + 1)));
;     p0 = __builtin_amdgcn_mfma_scale_f32_32x32x64_f8f6f4(a0, qf[s], p0, 0, 0, 0, 127, 0, 124);
;     p1 = __builtin_amdgcn_mfma_scale_f32_32x32x64_f8f6f4(a1, qf[s], p1, 0, 0, 0, 127, 0, 124); }
;   { const int c0 = hi * 2;
.Lmla_h1_cont:
	global_load_dwordx4 v[158:161], v176, s[18:19]
	global_load_dwordx4 v[162:165], v178, s[16:17]
	global_load_dwordx4 v[154:157], v[180:181], off
	ds_read_b128 v[114:117], v166 offset:24576
	ds_read_b128 v[118:121], v167 offset:24576
	ds_read_b128 v[222:225], v166 offset:28672
	ds_read_b128 v[226:229], v167 offset:28672
	v_add_u32_e32 v176, 0x2000, v176
	v_add_u32_e32 v178, 0x20000, v178
	s_mov_b64 s[20:21], 0x1000
	v_lshl_add_u64 v[180:181], v[180:181], 0, s[20:21]
	v_exp_f32_e32 v0, v82
	v_exp_f32_e32 v177, v83
	v_exp_f32_e32 v179, v84
	v_exp_f32_e32 v254, v85
	v_add_f32_e32 v219, v0, v177
	v_cvt_pk_fp8_f32 v246, v0, v177
	v_add_f32_e32 v219, v179, v219
	v_add_f32_e32 v219, v254, v219
	v_cvt_pk_fp8_f32 v246, v179, v254 op_sel:[0,0,1]
	s_waitcnt lgkmcnt(2)
	v_mfma_scale_f32_32x32x64_f8f6f4 v[114:129], v[114:121], v[146:153], v[230:245], v194, v193 op_sel_hi:[0,0,0]
	v_exp_f32_e32 v0, v86
	v_exp_f32_e32 v177, v87
	v_exp_f32_e32 v179, v88
	v_exp_f32_e32 v254, v89
	v_add_f32_e32 v219, v0, v219
	v_add_f32_e32 v219, v177, v219
	v_cvt_pk_fp8_f32 v247, v0, v177
	v_add_f32_e32 v219, v179, v219
	v_add_f32_e32 v219, v254, v219
	v_cvt_pk_fp8_f32 v247, v179, v254 op_sel:[0,0,1]
	ds_read_b128 v[82:85], v168 offset:24576
	ds_read_b128 v[86:89], v169 offset:24576
	s_waitcnt lgkmcnt(2)
	v_mfma_scale_f32_32x32x64_f8f6f4 v[98:113], v[222:229], v[146:153], v[230:245], v194, v193 op_sel_hi:[0,0,0]
	ds_read_b128 v[222:225], v168 offset:28672
	ds_read_b128 v[226:229], v169 offset:28672
	v_exp_f32_e32 v0, v90
	v_exp_f32_e32 v177, v91
	v_exp_f32_e32 v179, v92
	v_exp_f32_e32 v254, v93
	v_add_f32_e32 v219, v0, v219
	v_add_f32_e32 v219, v177, v219
	v_cvt_pk_fp8_f32 v248, v0, v177
	v_add_f32_e32 v219, v179, v219
	v_add_f32_e32 v219, v254, v219
	v_cvt_pk_fp8_f32 v248, v179, v254 op_sel:[0,0,1]
	v_exp_f32_e32 v0, v94
	v_exp_f32_e32 v177, v95
	v_exp_f32_e32 v179, v96
	v_exp_f32_e32 v254, v97
	v_add_f32_e32 v219, v0, v219
	v_add_f32_e32 v219, v177, v219
	v_cvt_pk_fp8_f32 v249, v0, v177
	v_add_f32_e32 v219, v179, v219
	v_add_f32_e32 v219, v254, v219
	v_cvt_pk_fp8_f32 v249, v179, v254 op_sel:[0,0,1]
	ds_read_b128 v[90:93], v170 offset:36864
	ds_read_b128 v[94:97], v171 offset:36864
	s_waitcnt lgkmcnt(4)
	v_mfma_scale_f32_32x32x64_f8f6f4 v[114:129], v[82:89], v[138:145], v[114:129], v194, v193 op_sel_hi:[0,0,0]
	v_exp_f32_e32 v0, v66
	v_exp_f32_e32 v177, v67
	v_exp_f32_e32 v179, v68
	v_exp_f32_e32 v254, v69
	v_add_f32_e32 v219, v0, v219
	v_add_f32_e32 v219, v177, v219
	v_cvt_pk_fp8_f32 v250, v0, v177
	v_add_f32_e32 v219, v179, v219
	v_add_f32_e32 v219, v254, v219
	v_cvt_pk_fp8_f32 v250, v179, v254 op_sel:[0,0,1]
	s_waitcnt lgkmcnt(2)
	v_mfma_scale_f32_32x32x64_f8f6f4 v[98:113], v[222:229], v[138:145], v[98:113], v194, v193 op_sel_hi:[0,0,0]
	ds_read_b128 v[222:225], v170 offset:38912
	ds_read_b128 v[226:229], v171 offset:38912
	v_exp_f32_e32 v0, v70
	v_exp_f32_e32 v177, v71
	v_exp_f32_e32 v179, v72
	v_exp_f32_e32 v254, v73
	v_add_f32_e32 v219, v0, v219
	v_add_f32_e32 v219, v177, v219
	v_cvt_pk_fp8_f32 v251, v0, v177
	v_add_f32_e32 v219, v179, v219
	v_add_f32_e32 v219, v254, v219
	v_cvt_pk_fp8_f32 v251, v179, v254 op_sel:[0,0,1]
	v_exp_f32_e32 v0, v74
	v_exp_f32_e32 v177, v75
	v_exp_f32_e32 v179, v76
	v_exp_f32_e32 v254, v77
	v_add_f32_e32 v219, v0, v219
	v_add_f32_e32 v219, v177, v219
	v_cvt_pk_fp8_f32 v252, v0, v177
	v_add_f32_e32 v219, v179, v219
	v_add_f32_e32 v219, v254, v219
	v_cvt_pk_fp8_f32 v252, v179, v254 op_sel:[0,0,1]
	s_waitcnt lgkmcnt(2)
	v_mfma_scale_f32_32x32x64_f8f6f4 v[114:129], v[90:97], v[130:137], v[114:129], v194, v193 op_sel_hi:[0,0,0]
	v_exp_f32_e32 v0, v78
	v_exp_f32_e32 v177, v79
	v_exp_f32_e32 v179, v80
	v_exp_f32_e32 v254, v81
	v_add_f32_e32 v219, v0, v219
	v_add_f32_e32 v219, v177, v219
	v_cvt_pk_fp8_f32 v253, v0, v177
	v_add_f32_e32 v219, v179, v219
	v_add_f32_e32 v219, v254, v219
	v_cvt_pk_fp8_f32 v253, v179, v254 op_sel:[0,0,1]
	ds_read_b128 v[90:93], v170 offset:0
	ds_read_b128 v[94:97], v171 offset:0
	ds_read_b128 v[82:85], v170 offset:2048
	ds_read_b128 v[86:89], v171 offset:2048
	ds_read_b128 v[74:77], v170 offset:4096
	ds_read_b128 v[78:81], v171 offset:4096
	ds_read_b128 v[66:69], v170 offset:6144
	ds_read_b128 v[70:73], v171 offset:6144
	s_waitcnt lgkmcnt(8)
	v_mfma_scale_f32_32x32x64_f8f6f4 v[98:113], v[222:229], v[130:137], v[98:113], v194, v193 op_sel_hi:[0,0,0]
	v_mov_b32_e32 v0, v219
	s_nop 1
	v_permlane32_swap_b32_e32 v219, v0
	v_add_f32_e32 v219, v219, v0
	v_fma_f32 v209, v209, v218, v219
	v_max_f32_e32 v177, v114, v115
	v_max3_f32 v177, v177, v116, v117
	v_max3_f32 v177, v177, v118, v119
	v_max3_f32 v177, v177, v120, v121
	v_max3_f32 v177, v177, v122, v123
	v_max3_f32 v177, v177, v124, v125
	v_max3_f32 v177, v177, v126, v127
	v_max3_f32 v177, v177, v128, v129
	s_waitcnt lgkmcnt(6)
	v_mfma_scale_f32_32x32x64_f8f6f4 v[50:65], v[246:253], v[90:97], v[50:65], v194, v194 op_sel_hi:[0,0,0]
	s_waitcnt lgkmcnt(4)
	v_mfma_scale_f32_32x32x64_f8f6f4 v[34:49], v[246:253], v[82:89], v[34:49], v194, v194 op_sel_hi:[0,0,0]
	s_waitcnt lgkmcnt(2)
	v_mfma_scale_f32_32x32x64_f8f6f4 v[18:33], v[246:253], v[74:81], v[18:33], v194, v194 op_sel_hi:[0,0,0]
	s_waitcnt vmcnt(0)
	ds_write_b128 v210, v[158:161]
	ds_write_b128 v211, v[162:165] offset:16384
	ds_write_b128 v212, v[154:157] offset:32768
	s_waitcnt lgkmcnt(3)
	v_mfma_scale_f32_32x32x64_f8f6f4 v[2:17], v[246:253], v[66:73], v[2:17], v194, v194 op_sel_hi:[0,0,0]
	s_waitcnt lgkmcnt(0)
	s_barrier
	v_max_f32_e32 v0, v98, v99
	v_max3_f32 v0, v0, v100, v101
	v_max3_f32 v0, v0, v102, v103
	v_max3_f32 v0, v0, v104, v105
	v_max3_f32 v0, v0, v106, v107
	v_max3_f32 v0, v0, v108, v109
	v_max3_f32 v0, v0, v110, v111
	v_max3_f32 v0, v0, v112, v113
	v_max_f32_e32 v177, v177, v0
	v_mov_b32_e32 v0, v177
	v_mov_b32_e32 v221, 1.0
	s_nop 0
	v_permlane32_swap_b32_e32 v177, v0
	v_max_f32_e32 v177, v177, v0
	v_cmp_ge_f32_e32 vcc, s90, v177
	s_cmp_eq_u64 vcc, exec
	s_cbranch_scc0 .Lmla_h2_newmax
; __device__ __forceinline__ void finishSM9(f32x16& p0, f32x16& p1, float alpha, float& l_reg, v8i32& p8) {
; #pragma unroll
;   for (int r = 0; r < 16; ++r) { p0[r] = __builtin_amdgcn_exp2f(p0[r]); p1[r] = __builtin_amdgcn_exp2f(p1[r]); }
;   float ps = 0;
; #pragma unroll
;   for (int r = 0; r < 16; ++r) ps += p0[r];
; #pragma unroll
;   for (int r = 0; r < 16; ++r) ps += p1[r];
;   { auto rr = __builtin_amdgcn_permlane32_swap(__float_as_uint(ps), __float_as_uint(ps), false, false);
;     ps = __uint_as_float(rr[0]) + __uint_as_float(rr[1]); }
;   l_reg = l_reg * alpha + ps;
; #pragma unroll
;   for (int g = 0; g < 4; ++g) {
;     int w = __builtin_amdgcn_cvt_pk_fp8_f32(p0[4 * g], p0[4 * g + 1], 0, false); p8[g] = __builtin_amdgcn_cvt_pk_fp8_f32(p0[4 * g + 2], p0[4 * g + 3], w, true);
;     int u = __builtin_amdgcn_cvt_pk_fp8_f32(p1[4 * g], p1[4 * g + 1], 0, false); p8[4 + g] = __builtin_amdgcn_cvt_pk_fp8_f32(p1[4 * g + 2], p1[4 * g + 3], u, true); }
; }
; __device__ __forceinline__ void pv8(f32x16* o, const char* Vt, const v8i32 p8, int r32, int hi) {
;   const int sw = (r32 >> 2) & 3, a0 = r32 * 64 + (((hi * 2) ^ sw) << 4), a1 = r32 * 64 + (((hi * 2 + 1) ^ sw) << 4);
; #pragma unroll
;   for (int d0 = 0; d0 < 4; ++d0) {
;     const v8i32 vf = cat8(*reinterpret_cast<const v4i32*>(Vt + d0 * 2048 + a0), *reinterpret_cast<const v4i32*>(Vt + d0 * 2048 + a1));
;     o[d0] = __builtin_amdgcn_mfma_scale_f32_32x32x64_f8f6f4(p8, vf, o[d0], 0, 0, 0, 127, 0, 127); }
; }
; __device__ __forceinline__ void qkt9(f32x16& p0, f32x16& p1, const char* Kn, const char* Kr, const v8i32* qf, const float init, int r32, int hi) {
; #pragma unroll
;   for (int r = 0; r < 16; ++r) { p0[r] = init; p1[r] = init; }
; #pragma unroll
;   for (int s = 0; s < 2; ++s) { const int c0 = s * 4 + hi * 2;
;     const v8i32 a0 = cat8(*reinterpret_cast<const v4i32*>(Kn + KN8SW(r32, c0)), *reinterpret_cast<const v4i32*>(Kn + KN8SW(r32, c0 + 1)));
;     const v8i32 a1 = cat8(*reinterpret_cast<const v4i32*>(Kn + 4096 + KN8SW(r32, c0)), *reinterpret_cast<const v4i32*>(Kn + 4096 + KN8SW(r32, c0 + 1)));
;     p0 = __builtin_amdgcn_mfma_scale_f32_32x32x64_f8f6f4(a0, qf[s], p0, 0, 0, 0, 127, 0, 124);
;     p1 = __builtin_amdgcn_mfma_scale_f32_32x32x64_f8f6f4(a1, qf[s], p1, 0, 0, 0, 127, 0, 124); }
;   { const int c0 = hi * 2;
.Lmla_h2_cont:
	global_load_dwordx4 v[158:161], v176, s[18:19]
	global_load_dwordx4 v[162:165], v178, s[16:17]
	global_load_dwordx4 v[154:157], v[180:181], off
	ds_read_b128 v[82:85], v215 offset:16384
	ds_read_b128 v[86:89], v216 offset:16384
	ds_read_b128 v[222:225], v215 offset:20480
	ds_read_b128 v[226:229], v216 offset:20480
	v_add_u32_e32 v176, 0x2000, v176
	v_add_u32_e32 v178, 0x20000, v178
	s_mov_b64 s[20:21], 0x1000
	v_lshl_add_u64 v[180:181], v[180:181], 0, s[20:21]
	v_exp_f32_e32 v0, v114
	v_exp_f32_e32 v177, v115
	v_exp_f32_e32 v179, v116
	v_exp_f32_e32 v254, v117
	v_add_f32_e32 v219, v0, v177
	v_cvt_pk_fp8_f32 v246, v0, v177
	v_add_f32_e32 v219, v179, v219
	v_add_f32_e32 v219, v254, v219
	v_cvt_pk_fp8_f32 v246, v179, v254 op_sel:[0,0,1]
	s_waitcnt lgkmcnt(2)
	v_mfma_scale_f32_32x32x64_f8f6f4 v[82:97], v[82:89], v[146:153], v[230:245], v194, v193 op_sel_hi:[0,0,0]
	v_exp_f32_e32 v0, v118
	v_exp_f32_e32 v177, v119
	v_exp_f32_e32 v179, v120
	v_exp_f32_e32 v254, v121
	v_add_f32_e32 v219, v0, v219
	v_add_f32_e32 v219, v177, v219
	v_cvt_pk_fp8_f32 v247, v0, v177
	v_add_f32_e32 v219, v179, v219
	v_add_f32_e32 v219, v254, v219
	v_cvt_pk_fp8_f32 v247, v179, v254 op_sel:[0,0,1]
	ds_read_b128 v[114:117], v213 offset:16384
	ds_read_b128 v[118:121], v214 offset:16384
	s_waitcnt lgkmcnt(2)
	v_mfma_scale_f32_32x32x64_f8f6f4 v[66:81], v[222:229], v[146:153], v[230:245], v194, v193 op_sel_hi:[0,0,0]
	ds_read_b128 v[222:225], v213 offset:20480
	ds_read_b128 v[226:229], v214 offset:20480
	v_exp_f32_e32 v0, v122
	v_exp_f32_e32 v177, v123
	v_exp_f32_e32 v179, v124
	v_exp_f32_e32 v254, v125
	v_add_f32_e32 v219, v0, v219
	v_add_f32_e32 v219, v177, v219
	v_cvt_pk_fp8_f32 v248, v0, v177
	v_add_f32_e32 v219, v179, v219
	v_add_f32_e32 v219, v254, v219
	v_cvt_pk_fp8_f32 v248, v179, v254 op_sel:[0,0,1]
	v_exp_f32_e32 v0, v126
	v_exp_f32_e32 v177, v127
	v_exp_f32_e32 v179, v128
	v_exp_f32_e32 v254, v129
	v_add_f32_e32 v219, v0, v219
	v_add_f32_e32 v219, v177, v219
	v_cvt_pk_fp8_f32 v249, v0, v177
	v_add_f32_e32 v219, v179, v219
	v_add_f32_e32 v219, v254, v219
	v_cvt_pk_fp8_f32 v249, v179, v254 op_sel:[0,0,1]
	ds_read_b128 v[122:125], v185 offset:32768
	ds_read_b128 v[126:129], v186 offset:32768
	s_waitcnt lgkmcnt(4)
	v_mfma_scale_f32_32x32x64_f8f6f4 v[82:97], v[114:121], v[138:145], v[82:97], v194, v193 op_sel_hi:[0,0,0]
	v_exp_f32_e32 v0, v98
	v_exp_f32_e32 v177, v99
	v_exp_f32_e32 v179, v100
	v_exp_f32_e32 v254, v101
	v_add_f32_e32 v219, v0, v219
	v_add_f32_e32 v219, v177, v219
	v_cvt_pk_fp8_f32 v250, v0, v177
	v_add_f32_e32 v219, v179, v219
	v_add_f32_e32 v219, v254, v219
	v_cvt_pk_fp8_f32 v250, v179, v254 op_sel:[0,0,1]
	s_waitcnt lgkmcnt(2)
	v_mfma_scale_f32_32x32x64_f8f6f4 v[66:81], v[222:229], v[138:145], v[66:81], v194, v193 op_sel_hi:[0,0,0]
	ds_read_b128 v[222:225], v185 offset:34816
	ds_read_b128 v[226:229], v186 offset:34816
	v_exp_f32_e32 v0, v102
	v_exp_f32_e32 v177, v103
	v_exp_f32_e32 v179, v104
	v_exp_f32_e32 v254, v105
	v_add_f32_e32 v219, v0, v219
	v_add_f32_e32 v219, v177, v219
	v_cvt_pk_fp8_f32 v251, v0, v177
	v_add_f32_e32 v219, v179, v219
	v_add_f32_e32 v219, v254, v219
	v_cvt_pk_fp8_f32 v251, v179, v254 op_sel:[0,0,1]
	v_exp_f32_e32 v0, v106
	v_exp_f32_e32 v177, v107
	v_exp_f32_e32 v179, v108
	v_exp_f32_e32 v254, v109
	v_add_f32_e32 v219, v0, v219
	v_add_f32_e32 v219, v177, v219
	v_cvt_pk_fp8_f32 v252, v0, v177
	v_add_f32_e32 v219, v179, v219
	v_add_f32_e32 v219, v254, v219
	v_cvt_pk_fp8_f32 v252, v179, v254 op_sel:[0,0,1]
	s_waitcnt lgkmcnt(2)
	v_mfma_scale_f32_32x32x64_f8f6f4 v[82:97], v[122:129], v[130:137], v[82:97], v194, v193 op_sel_hi:[0,0,0]
	v_exp_f32_e32 v0, v110
	v_exp_f32_e32 v177, v111
	v_exp_f32_e32 v179, v112
	v_exp_f32_e32 v254, v113
	v_add_f32_e32 v219, v0, v219
	v_add_f32_e32 v219, v177, v219
	v_cvt_pk_fp8_f32 v253, v0, v177
	v_add_f32_e32 v219, v179, v219
	v_add_f32_e32 v219, v254, v219
	v_cvt_pk_fp8_f32 v253, v179, v254 op_sel:[0,0,1]
	ds_read_b128 v[122:125], v170 offset:8192
	ds_read_b128 v[126:129], v171 offset:8192
	ds_read_b128 v[114:117], v170 offset:10240
	ds_read_b128 v[118:121], v171 offset:10240
	ds_read_b128 v[106:109], v170 offset:12288
	ds_read_b128 v[110:113], v171 offset:12288
	ds_read_b128 v[98:101], v170 offset:14336
	ds_read_b128 v[102:105], v171 offset:14336
	s_waitcnt lgkmcnt(8)
	v_mfma_scale_f32_32x32x64_f8f6f4 v[66:81], v[222:229], v[130:137], v[66:81], v194, v193 op_sel_hi:[0,0,0]
	v_mov_b32_e32 v0, v219
	s_nop 1
	v_permlane32_swap_b32_e32 v219, v0
	v_add_f32_e32 v219, v219, v0
	v_fma_f32 v209, v209, v221, v219
	v_max_f32_e32 v177, v82, v83
	v_max3_f32 v177, v177, v84, v85
	v_max3_f32 v177, v177, v86, v87
	v_max3_f32 v177, v177, v88, v89
	v_max3_f32 v177, v177, v90, v91
	v_max3_f32 v177, v177, v92, v93
	v_max3_f32 v177, v177, v94, v95
	v_max3_f32 v177, v177, v96, v97
	s_waitcnt lgkmcnt(6)
	v_mfma_scale_f32_32x32x64_f8f6f4 v[50:65], v[246:253], v[122:129], v[50:65], v194, v194 op_sel_hi:[0,0,0]
	s_waitcnt lgkmcnt(4)
	v_mfma_scale_f32_32x32x64_f8f6f4 v[34:49], v[246:253], v[114:121], v[34:49], v194, v194 op_sel_hi:[0,0,0]
	s_waitcnt lgkmcnt(2)
	v_mfma_scale_f32_32x32x64_f8f6f4 v[18:33], v[246:253], v[106:113], v[18:33], v194, v194 op_sel_hi:[0,0,0]
	s_waitcnt vmcnt(0)
	ds_write_b128 v210, v[158:161] offset:8192
	ds_write_b128 v211, v[162:165] offset:24576
	ds_write_b128 v212, v[154:157] offset:36864
	s_waitcnt lgkmcnt(3)
	v_mfma_scale_f32_32x32x64_f8f6f4 v[2:17], v[246:253], v[98:105], v[2:17], v194, v194 op_sel_hi:[0,0,0]
	s_waitcnt lgkmcnt(0)
	s_barrier
	v_max_f32_e32 v0, v66, v67
	v_max3_f32 v0, v0, v68, v69
	v_max3_f32 v0, v0, v70, v71
	v_max3_f32 v0, v0, v72, v73
	v_max3_f32 v0, v0, v74, v75
	v_max3_f32 v0, v0, v76, v77
	v_max3_f32 v0, v0, v78, v79
	v_max3_f32 v0, v0, v80, v81
	v_max_f32_e32 v177, v177, v0
	v_mov_b32_e32 v0, v177
	v_mov_b32_e32 v218, 1.0
	s_nop 0
	v_permlane32_swap_b32_e32 v177, v0
	v_max_f32_e32 v177, v177, v0
	v_cmp_ge_f32_e32 vcc, s90, v177
	s_cmp_eq_u64 vcc, exec
	s_cbranch_scc0 .Lmla_h3_newmax
; __device__ __forceinline__ void finishSM9(f32x16& p0, f32x16& p1, float alpha, float& l_reg, v8i32& p8) {
; #pragma unroll
;   for (int r = 0; r < 16; ++r) { p0[r] = __builtin_amdgcn_exp2f(p0[r]); p1[r] = __builtin_amdgcn_exp2f(p1[r]); }
;   float ps = 0;
; #pragma unroll
;   for (int r = 0; r < 16; ++r) ps += p0[r];
; #pragma unroll
;   for (int r = 0; r < 16; ++r) ps += p1[r];
;   { auto rr = __builtin_amdgcn_permlane32_swap(__float_as_uint(ps), __float_as_uint(ps), false, false);
;     ps = __uint_as_float(rr[0]) + __uint_as_float(rr[1]); }
;   l_reg = l_reg * alpha + ps;
; #pragma unroll
;   for (int g = 0; g < 4; ++g) {
;     int w = __builtin_amdgcn_cvt_pk_fp8_f32(p0[4 * g], p0[4 * g + 1], 0, false); p8[g] = __builtin_amdgcn_cvt_pk_fp8_f32(p0[4 * g + 2], p0[4 * g + 3], w, true);
;     int u = __builtin_amdgcn_cvt_pk_fp8_f32(p1[4 * g], p1[4 * g + 1], 0, false); p8[4 + g] = __builtin_amdgcn_cvt_pk_fp8_f32(p1[4 * g + 2], p1[4 * g + 3], u, true); }
; }
; __device__ __forceinline__ void pv8(f32x16* o, const char* Vt, const v8i32 p8, int r32, int hi) {
;   const int sw = (r32 >> 2) & 3, a0 = r32 * 64 + (((hi * 2) ^ sw) << 4), a1 = r32 * 64 + (((hi * 2 + 1) ^ sw) << 4);
; #pragma unroll
;   for (int d0 = 0; d0 < 4; ++d0) {
;     const v8i32 vf = cat8(*reinterpret_cast<const v4i32*>(Vt + d0 * 2048 + a0), *reinterpret_cast<const v4i32*>(Vt + d0 * 2048 + a1));
;     o[d0] = __builtin_amdgcn_mfma_scale_f32_32x32x64_f8f6f4(p8, vf, o[d0], 0, 0, 0, 127, 0, 127); }
; }
; __device__ __forceinline__ void qkt9(f32x16& p0, f32x16& p1, const char* Kn, const char* Kr, const v8i32* qf, const float init, int r32, int hi) {
; #pragma unroll
;   for (int r = 0; r < 16; ++r) { p0[r] = init; p1[r] = init; }
; #pragma unroll
;   for (int s = 0; s < 2; ++s) { const int c0 = s * 4 + hi * 2;
;     const v8i32 a0 = cat8(*reinterpret_cast<const v4i32*>(Kn + KN8SW(r32, c0)), *reinterpret_cast<const v4i32*>(Kn + KN8SW(r32, c0 + 1)));
;     const v8i32 a1 = cat8(*reinterpret_cast<const v4i32*>(Kn + 4096 + KN8SW(r32, c0)), *reinterpret_cast<const v4i32*>(Kn + 4096 + KN8SW(r32, c0 + 1)));
;     p0 = __builtin_amdgcn_mfma_scale_f32_32x32x64_f8f6f4(a0, qf[s], p0, 0, 0, 0, 127, 0, 124);
;     p1 = __builtin_amdgcn_mfma_scale_f32_32x32x64_f8f6f4(a1, qf[s], p1, 0, 0, 0, 127, 0, 124); }
;   { const int c0 = hi * 2;
.Lmla_h3_cont:
	s_add_i32 s30, s30, 1
	s_cmpk_lt_u32 s30, 63
	s_cbranch_scc1 .LBB0_1321
	global_load_dwordx4 v[158:161], v176, s[18:19]
	global_load_dwordx4 v[162:165], v178, s[16:17]
	global_load_dwordx4 v[154:157], v[180:181], off
	ds_read_b128 v[114:117], v215 offset:24576
	ds_read_b128 v[118:121], v216 offset:24576
	ds_read_b128 v[222:225], v215 offset:28672
	ds_read_b128 v[226:229], v216 offset:28672
	v_add_u32_e32 v176, 0x2000, v176
	v_add_u32_e32 v178, 0x20000, v178
	s_mov_b64 s[20:21], 0x1000
	v_lshl_add_u64 v[180:181], v[180:181], 0, s[20:21]
	v_exp_f32_e32 v0, v82
	v_exp_f32_e32 v177, v83
	v_exp_f32_e32 v179, v84
	v_exp_f32_e32 v254, v85
	v_add_f32_e32 v219, v0, v177
	v_cvt_pk_fp8_f32 v246, v0, v177
	v_add_f32_e32 v219, v179, v219
	v_add_f32_e32 v219, v254, v219
	v_cvt_pk_fp8_f32 v246, v179, v254 op_sel:[0,0,1]
	s_waitcnt lgkmcnt(2)
	v_mfma_scale_f32_32x32x64_f8f6f4 v[114:129], v[114:121], v[146:153], v[230:245], v194, v193 op_sel_hi:[0,0,0]
	v_exp_f32_e32 v0, v86
	v_exp_f32_e32 v177, v87
	v_exp_f32_e32 v179, v88
	v_exp_f32_e32 v254, v89
	v_add_f32_e32 v219, v0, v219
	v_add_f32_e32 v219, v177, v219
	v_cvt_pk_fp8_f32 v247, v0, v177
	v_add_f32_e32 v219, v179, v219
	v_add_f32_e32 v219, v254, v219
	v_cvt_pk_fp8_f32 v247, v179, v254 op_sel:[0,0,1]
	ds_read_b128 v[82:85], v213 offset:24576
	ds_read_b128 v[86:89], v214 offset:24576
	s_waitcnt lgkmcnt(2)
	v_mfma_scale_f32_32x32x64_f8f6f4 v[98:113], v[222:229], v[146:153], v[230:245], v194, v193 op_sel_hi:[0,0,0]
	ds_read_b128 v[222:225], v213 offset:28672
	ds_read_b128 v[226:229], v214 offset:28672
	v_exp_f32_e32 v0, v90
	v_exp_f32_e32 v177, v91
	v_exp_f32_e32 v179, v92
	v_exp_f32_e32 v254, v93
	v_add_f32_e32 v219, v0, v219
	v_add_f32_e32 v219, v177, v219
	v_cvt_pk_fp8_f32 v248, v0, v177
	v_add_f32_e32 v219, v179, v219
	v_add_f32_e32 v219, v254, v219
	v_cvt_pk_fp8_f32 v248, v179, v254 op_sel:[0,0,1]
	v_exp_f32_e32 v0, v94
	v_exp_f32_e32 v177, v95
	v_exp_f32_e32 v179, v96
	v_exp_f32_e32 v254, v97
	v_add_f32_e32 v219, v0, v219
	v_add_f32_e32 v219, v177, v219
	v_cvt_pk_fp8_f32 v249, v0, v177
	v_add_f32_e32 v219, v179, v219
	v_add_f32_e32 v219, v254, v219
	v_cvt_pk_fp8_f32 v249, v179, v254 op_sel:[0,0,1]
	ds_read_b128 v[90:93], v185 offset:36864
	ds_read_b128 v[94:97], v186 offset:36864
	s_waitcnt lgkmcnt(4)
	v_mfma_scale_f32_32x32x64_f8f6f4 v[114:129], v[82:89], v[138:145], v[114:129], v194, v193 op_sel_hi:[0,0,0]
	v_exp_f32_e32 v0, v66
	v_exp_f32_e32 v177, v67
	v_exp_f32_e32 v179, v68
	v_exp_f32_e32 v254, v69
	v_add_f32_e32 v219, v0, v219
	v_add_f32_e32 v219, v177, v219
	v_cvt_pk_fp8_f32 v250, v0, v177
	v_add_f32_e32 v219, v179, v219
	v_add_f32_e32 v219, v254, v219
	v_cvt_pk_fp8_f32 v250, v179, v254 op_sel:[0,0,1]
	s_waitcnt lgkmcnt(2)
	v_mfma_scale_f32_32x32x64_f8f6f4 v[98:113], v[222:229], v[138:145], v[98:113], v194, v193 op_sel_hi:[0,0,0]
	ds_read_b128 v[222:225], v185 offset:38912
	ds_read_b128 v[226:229], v186 offset:38912
	v_exp_f32_e32 v0, v70
	v_exp_f32_e32 v177, v71
	v_exp_f32_e32 v179, v72
	v_exp_f32_e32 v254, v73
	v_add_f32_e32 v219, v0, v219
	v_add_f32_e32 v219, v177, v219
	v_cvt_pk_fp8_f32 v251, v0, v177
	v_add_f32_e32 v219, v179, v219
	v_add_f32_e32 v219, v254, v219
	v_cvt_pk_fp8_f32 v251, v179, v254 op_sel:[0,0,1]
	v_exp_f32_e32 v0, v74
	v_exp_f32_e32 v177, v75
	v_exp_f32_e32 v179, v76
	v_exp_f32_e32 v254, v77
	v_add_f32_e32 v219, v0, v219
	v_add_f32_e32 v219, v177, v219
	v_cvt_pk_fp8_f32 v252, v0, v177
	v_add_f32_e32 v219, v179, v219
	v_add_f32_e32 v219, v254, v219
	v_cvt_pk_fp8_f32 v252, v179, v254 op_sel:[0,0,1]
	s_waitcnt lgkmcnt(2)
	v_mfma_scale_f32_32x32x64_f8f6f4 v[114:129], v[90:97], v[130:137], v[114:129], v194, v193 op_sel_hi:[0,0,0]
	v_exp_f32_e32 v0, v78
	v_exp_f32_e32 v177, v79
	v_exp_f32_e32 v179, v80
	v_exp_f32_e32 v254, v81
	v_add_f32_e32 v219, v0, v219
	v_add_f32_e32 v219, v177, v219
	v_cvt_pk_fp8_f32 v253, v0, v177
	v_add_f32_e32 v219, v179, v219
	v_add_f32_e32 v219, v254, v219
	v_cvt_pk_fp8_f32 v253, v179, v254 op_sel:[0,0,1]
	ds_read_b128 v[90:93], v185 offset:0
	ds_read_b128 v[94:97], v186 offset:0
	ds_read_b128 v[82:85], v185 offset:2048
	ds_read_b128 v[86:89], v186 offset:2048
	ds_read_b128 v[74:77], v185 offset:4096
	ds_read_b128 v[78:81], v186 offset:4096
	ds_read_b128 v[66:69], v185 offset:6144
	ds_read_b128 v[70:73], v186 offset:6144
	s_waitcnt lgkmcnt(8)
	v_mfma_scale_f32_32x32x64_f8f6f4 v[98:113], v[222:229], v[130:137], v[98:113], v194, v193 op_sel_hi:[0,0,0]
	v_mov_b32_e32 v0, v219
	s_nop 1
	v_permlane32_swap_b32_e32 v219, v0
	v_add_f32_e32 v219, v219, v0
	v_fma_f32 v209, v209, v218, v219
	v_max_f32_e32 v177, v114, v115
	v_max3_f32 v177, v177, v116, v117
	v_max3_f32 v177, v177, v118, v119
	v_max3_f32 v177, v177, v120, v121
	v_max3_f32 v177, v177, v122, v123
	v_max3_f32 v177, v177, v124, v125
	v_max3_f32 v177, v177, v126, v127
	v_max3_f32 v177, v177, v128, v129
	s_waitcnt lgkmcnt(6)
	v_mfma_scale_f32_32x32x64_f8f6f4 v[50:65], v[246:253], v[90:97], v[50:65], v194, v194 op_sel_hi:[0,0,0]
	s_waitcnt lgkmcnt(4)
	v_mfma_scale_f32_32x32x64_f8f6f4 v[34:49], v[246:253], v[82:89], v[34:49], v194, v194 op_sel_hi:[0,0,0]
	s_waitcnt lgkmcnt(2)
	v_mfma_scale_f32_32x32x64_f8f6f4 v[18:33], v[246:253], v[74:81], v[18:33], v194, v194 op_sel_hi:[0,0,0]
	s_waitcnt vmcnt(0)
	ds_write_b128 v172, v[158:161]
	ds_write_b128 v173, v[162:165] offset:16384
	ds_write_b128 v220, v[154:157] offset:32768
	s_waitcnt lgkmcnt(3)
	v_mfma_scale_f32_32x32x64_f8f6f4 v[2:17], v[246:253], v[66:73], v[2:17], v194, v194 op_sel_hi:[0,0,0]
	s_waitcnt lgkmcnt(0)
	s_barrier
	v_max_f32_e32 v0, v98, v99
	v_max3_f32 v0, v0, v100, v101
	v_max3_f32 v0, v0, v102, v103
	v_max3_f32 v0, v0, v104, v105
	v_max3_f32 v0, v0, v106, v107
	v_max3_f32 v0, v0, v108, v109
	v_max3_f32 v0, v0, v110, v111
	v_max3_f32 v0, v0, v112, v113
	v_max_f32_e32 v177, v177, v0
	v_mov_b32_e32 v0, v177
	v_mov_b32_e32 v221, 1.0
	s_nop 0
	v_permlane32_swap_b32_e32 v177, v0
	v_max_f32_e32 v177, v177, v0
	v_cmp_ge_f32_e32 vcc, s90, v177
	s_cmp_eq_u64 vcc, exec
	s_cbranch_scc0 .Lmla_p0_newmax

; __device__ __forceinline__ void finishSM9(f32x16& p0, f32x16& p1, float alpha, float& l_reg, v8i32& p8) {
; #pragma unroll
;   for (int r = 0; r < 16; ++r) { p0[r] = __builtin_amdgcn_exp2f(p0[r]); p1[r] = __builtin_amdgcn_exp2f(p1[r]); }
;   float ps = 0;
; #pragma unroll
;   for (int r = 0; r < 16; ++r) ps += p0[r];
; #pragma unroll
;   for (int r = 0; r < 16; ++r) ps += p1[r];
;   { auto rr = __builtin_amdgcn_permlane32_swap(__float_as_uint(ps), __float_as_uint(ps), false, false);
;     ps = __uint_as_float(rr[0]) + __uint_as_float(rr[1]); }
;   l_reg = l_reg * alpha + ps;
; #pragma unroll
;   for (int g = 0; g < 4; ++g) {
;     int w = __builtin_amdgcn_cvt_pk_fp8_f32(p0[4 * g], p0[4 * g + 1], 0, false); p8[g] = __builtin_amdgcn_cvt_pk_fp8_f32(p0[4 * g + 2], p0[4 * g + 3], w, true);
;     int u = __builtin_amdgcn_cvt_pk_fp8_f32(p1[4 * g], p1[4 * g + 1], 0, false); p8[4 + g] = __builtin_amdgcn_cvt_pk_fp8_f32(p1[4 * g + 2], p1[4 * g + 3], u, true); }
; }
; __device__ __forceinline__ void pv8(f32x16* o, const char* Vt, const v8i32 p8, int r32, int hi) {
;   const int sw = (r32 >> 2) & 3, a0 = r32 * 64 + (((hi * 2) ^ sw) << 4), a1 = r32 * 64 + (((hi * 2 + 1) ^ sw) << 4);
; #pragma unroll
;   for (int d0 = 0; d0 < 4; ++d0) {
;     const v8i32 vf = cat8(*reinterpret_cast<const v4i32*>(Vt + d0 * 2048 + a0), *reinterpret_cast<const v4i32*>(Vt + d0 * 2048 + a1));
;     o[d0] = __builtin_amdgcn_mfma_scale_f32_32x32x64_f8f6f4(p8, vf, o[d0], 0, 0, 0, 127, 0, 127); }
; }
; __device__ __forceinline__ void qkt9(f32x16& p0, f32x16& p1, const char* Kn, const char* Kr, const v8i32* qf, const float init, int r32, int hi) {
; #pragma unroll
;   for (int r = 0; r < 16; ++r) { p0[r] = init; p1[r] = init; }
; #pragma unroll
;   for (int s = 0; s < 2; ++s) { const int c0 = s * 4 + hi * 2;
;     const v8i32 a0 = cat8(*reinterpret_cast<const v4i32*>(Kn + KN8SW(r32, c0)), *reinterpret_cast<const v4i32*>(Kn + KN8SW(r32, c0 + 1)));
;     const v8i32 a1 = cat8(*reinterpret_cast<const v4i32*>(Kn + 4096 + KN8SW(r32, c0)), *reinterpret_cast<const v4i32*>(Kn + 4096 + KN8SW(r32, c0 + 1)));
;     p0 = __builtin_amdgcn_mfma_scale_f32_32x32x64_f8f6f4(a0, qf[s], p0, 0, 0, 0, 127, 0, 124);
;     p1 = __builtin_amdgcn_mfma_scale_f32_32x32x64_f8f6f4(a1, qf[s], p1, 0, 0, 0, 127, 0, 124); }
;   { const int c0 = hi * 2;
.Lmla_stag_loop:
	ds_read_b128 v[114:117], v215 offset:24576
	ds_read_b128 v[118:121], v216 offset:24576
	ds_read_b128 v[222:225], v215 offset:28672
	ds_read_b128 v[226:229], v216 offset:28672
	v_exp_f32_e32 v0, v82
	v_exp_f32_e32 v177, v83
	v_exp_f32_e32 v179, v84
	v_exp_f32_e32 v254, v85
	v_add_f32_e32 v219, v0, v177
	v_cvt_pk_fp8_f32 v246, v0, v177
	v_add_f32_e32 v219, v179, v219
	v_add_f32_e32 v219, v254, v219
	v_cvt_pk_fp8_f32 v246, v179, v254 op_sel:[0,0,1]
	s_waitcnt lgkmcnt(2)
	v_mfma_scale_f32_32x32x64_f8f6f4 v[114:129], v[114:121], v[146:153], v[230:245], v194, v193 op_sel_hi:[0,0,0]
	v_exp_f32_e32 v0, v86
	v_exp_f32_e32 v177, v87
	v_exp_f32_e32 v179, v88
	v_exp_f32_e32 v254, v89
	v_add_f32_e32 v219, v0, v219
	v_add_f32_e32 v219, v177, v219
	v_cvt_pk_fp8_f32 v247, v0, v177
	v_add_f32_e32 v219, v179, v219
	v_add_f32_e32 v219, v254, v219
	v_cvt_pk_fp8_f32 v247, v179, v254 op_sel:[0,0,1]
	ds_read_b128 v[82:85], v213 offset:24576
	ds_read_b128 v[86:89], v214 offset:24576
	s_waitcnt lgkmcnt(2)
	v_mfma_scale_f32_32x32x64_f8f6f4 v[98:113], v[222:229], v[146:153], v[230:245], v194, v193 op_sel_hi:[0,0,0]
	ds_read_b128 v[222:225], v213 offset:28672
	ds_read_b128 v[226:229], v214 offset:28672
	v_exp_f32_e32 v0, v90
	v_exp_f32_e32 v177, v91
	v_exp_f32_e32 v179, v92
	v_exp_f32_e32 v254, v93
	v_add_f32_e32 v219, v0, v219
	v_add_f32_e32 v219, v177, v219
	v_cvt_pk_fp8_f32 v248, v0, v177
	v_add_f32_e32 v219, v179, v219
	v_add_f32_e32 v219, v254, v219
	v_cvt_pk_fp8_f32 v248, v179, v254 op_sel:[0,0,1]
	v_exp_f32_e32 v0, v94
	v_exp_f32_e32 v177, v95
	v_exp_f32_e32 v179, v96
	v_exp_f32_e32 v254, v97
	v_add_f32_e32 v219, v0, v219
	v_add_f32_e32 v219, v177, v219
	v_cvt_pk_fp8_f32 v249, v0, v177
	v_add_f32_e32 v219, v179, v219
	v_add_f32_e32 v219, v254, v219
	v_cvt_pk_fp8_f32 v249, v179, v254 op_sel:[0,0,1]
	ds_read_b128 v[90:93], v185 offset:36864
	ds_read_b128 v[94:97], v186 offset:36864
	s_waitcnt vmcnt(0)
	ds_write_b128 v172, v[158:161]
	ds_write_b128 v173, v[162:165] offset:16384
	s_waitcnt lgkmcnt(6)
	v_mfma_scale_f32_32x32x64_f8f6f4 v[114:129], v[82:89], v[138:145], v[114:129], v194, v193 op_sel_hi:[0,0,0]
	s_waitcnt lgkmcnt(0)
	s_barrier
	global_load_dwordx4 v[158:161], v176, s[18:19]
	global_load_dwordx4 v[162:165], v178, s[16:17]
	v_add_u32_e32 v176, 0x2000, v176
	v_add_u32_e32 v178, 0x20000, v178
	v_exp_f32_e32 v0, v66
	v_exp_f32_e32 v177, v67
	v_exp_f32_e32 v179, v68
	v_exp_f32_e32 v254, v69
	v_add_f32_e32 v219, v0, v219
	v_add_f32_e32 v219, v177, v219
	v_cvt_pk_fp8_f32 v250, v0, v177
	v_add_f32_e32 v219, v179, v219
	v_add_f32_e32 v219, v254, v219
	v_cvt_pk_fp8_f32 v250, v179, v254 op_sel:[0,0,1]
	s_waitcnt lgkmcnt(2)
	v_mfma_scale_f32_32x32x64_f8f6f4 v[98:113], v[222:229], v[138:145], v[98:113], v194, v193 op_sel_hi:[0,0,0]
	ds_read_b128 v[222:225], v185 offset:38912
	ds_read_b128 v[226:229], v186 offset:38912
	v_exp_f32_e32 v0, v70
	v_exp_f32_e32 v177, v71
	v_exp_f32_e32 v179, v72
	v_exp_f32_e32 v254, v73
	v_add_f32_e32 v219, v0, v219
	v_add_f32_e32 v219, v177, v219
	v_cvt_pk_fp8_f32 v251, v0, v177
	v_add_f32_e32 v219, v179, v219
	v_add_f32_e32 v219, v254, v219
	v_cvt_pk_fp8_f32 v251, v179, v254 op_sel:[0,0,1]
	v_exp_f32_e32 v0, v74
	v_exp_f32_e32 v177, v75
	v_exp_f32_e32 v179, v76
	v_exp_f32_e32 v254, v77
	v_add_f32_e32 v219, v0, v219
	v_add_f32_e32 v219, v177, v219
	v_cvt_pk_fp8_f32 v252, v0, v177
	v_add_f32_e32 v219, v179, v219
	v_add_f32_e32 v219, v254, v219
	v_cvt_pk_fp8_f32 v252, v179, v254 op_sel:[0,0,1]
	s_waitcnt lgkmcnt(2)
	v_mfma_scale_f32_32x32x64_f8f6f4 v[114:129], v[90:97], v[130:137], v[114:129], v194, v193 op_sel_hi:[0,0,0]
	v_exp_f32_e32 v0, v78
	v_exp_f32_e32 v177, v79
	v_exp_f32_e32 v179, v80
	v_exp_f32_e32 v254, v81
	v_add_f32_e32 v219, v0, v219
	v_add_f32_e32 v219, v177, v219
	v_cvt_pk_fp8_f32 v253, v0, v177
	v_add_f32_e32 v219, v179, v219
	v_add_f32_e32 v219, v254, v219
	v_cvt_pk_fp8_f32 v253, v179, v254 op_sel:[0,0,1]
	ds_read_b128 v[90:93], v185 offset:0
	ds_read_b128 v[94:97], v186 offset:0
	ds_read_b128 v[82:85], v185 offset:2048
	ds_read_b128 v[86:89], v186 offset:2048
	ds_read_b128 v[74:77], v185 offset:4096
	ds_read_b128 v[78:81], v186 offset:4096
	ds_read_b128 v[66:69], v185 offset:6144
	ds_read_b128 v[70:73], v186 offset:6144
	s_waitcnt lgkmcnt(8)
	v_mfma_scale_f32_32x32x64_f8f6f4 v[98:113], v[222:229], v[130:137], v[98:113], v194, v193 op_sel_hi:[0,0,0]
	v_mov_b32_e32 v0, v219
	s_nop 1
	v_permlane32_swap_b32_e32 v219, v0
	v_add_f32_e32 v219, v219, v0
	v_fma_f32 v209, v209, v218, v219
	v_max_f32_e32 v177, v114, v115
	v_max3_f32 v177, v177, v116, v117
	v_max3_f32 v177, v177, v118, v119
	v_max3_f32 v177, v177, v120, v121
	v_max3_f32 v177, v177, v122, v123
	v_max3_f32 v177, v177, v124, v125
	v_max3_f32 v177, v177, v126, v127
	v_max3_f32 v177, v177, v128, v129
	s_waitcnt lgkmcnt(6)
	v_mfma_scale_f32_32x32x64_f8f6f4 v[50:65], v[246:253], v[90:97], v[50:65], v194, v194 op_sel_hi:[0,0,0]
	s_waitcnt lgkmcnt(4)
	v_mfma_scale_f32_32x32x64_f8f6f4 v[34:49], v[246:253], v[82:89], v[34:49], v194, v194 op_sel_hi:[0,0,0]
	s_waitcnt lgkmcnt(2)
	v_mfma_scale_f32_32x32x64_f8f6f4 v[18:33], v[246:253], v[74:81], v[18:33], v194, v194 op_sel_hi:[0,0,0]
	s_waitcnt lgkmcnt(0)
	v_mfma_scale_f32_32x32x64_f8f6f4 v[2:17], v[246:253], v[66:73], v[2:17], v194, v194 op_sel_hi:[0,0,0]
	v_max_f32_e32 v0, v98, v99
	v_max3_f32 v0, v0, v100, v101
	v_max3_f32 v0, v0, v102, v103
	v_max3_f32 v0, v0, v104, v105
	v_max3_f32 v0, v0, v106, v107
	v_max3_f32 v0, v0, v108, v109
	v_max3_f32 v0, v0, v110, v111
	v_max3_f32 v0, v0, v112, v113
	v_max_f32_e32 v177, v177, v0
	v_mov_b32_e32 v0, v177
	v_mov_b32_e32 v221, 1.0
	s_nop 0
	v_permlane32_swap_b32_e32 v177, v0
	v_max_f32_e32 v177, v177, v0
	v_cmp_ge_f32_e32 vcc, s90, v177
	s_cmp_eq_u64 vcc, exec
	s_cbranch_scc0 .Lmla_s0_newmax
; __device__ __forceinline__ void finishSM9(f32x16& p0, f32x16& p1, float alpha, float& l_reg, v8i32& p8) {
; #pragma unroll
;   for (int r = 0; r < 16; ++r) { p0[r] = __builtin_amdgcn_exp2f(p0[r]); p1[r] = __builtin_amdgcn_exp2f(p1[r]); }
;   float ps = 0;
; #pragma unroll
;   for (int r = 0; r < 16; ++r) ps += p0[r];
; #pragma unroll
;   for (int r = 0; r < 16; ++r) ps += p1[r];
;   { auto rr = __builtin_amdgcn_permlane32_swap(__float_as_uint(ps), __float_as_uint(ps), false, false);
;     ps = __uint_as_float(rr[0]) + __uint_as_float(rr[1]); }
;   l_reg = l_reg * alpha + ps;
; #pragma unroll
;   for (int g = 0; g < 4; ++g) {
;     int w = __builtin_amdgcn_cvt_pk_fp8_f32(p0[4 * g], p0[4 * g + 1], 0, false); p8[g] = __builtin_amdgcn_cvt_pk_fp8_f32(p0[4 * g + 2], p0[4 * g + 3], w, true);
;     int u = __builtin_amdgcn_cvt_pk_fp8_f32(p1[4 * g], p1[4 * g + 1], 0, false); p8[4 + g] = __builtin_amdgcn_cvt_pk_fp8_f32(p1[4 * g + 2], p1[4 * g + 3], u, true); }
; }
; __device__ __forceinline__ void pv8(f32x16* o, const char* Vt, const v8i32 p8, int r32, int hi) {
;   const int sw = (r32 >> 2) & 3, a0 = r32 * 64 + (((hi * 2) ^ sw) << 4), a1 = r32 * 64 + (((hi * 2 + 1) ^ sw) << 4);
; #pragma unroll
;   for (int d0 = 0; d0 < 4; ++d0) {
;     const v8i32 vf = cat8(*reinterpret_cast<const v4i32*>(Vt + d0 * 2048 + a0), *reinterpret_cast<const v4i32*>(Vt + d0 * 2048 + a1));
;     o[d0] = __builtin_amdgcn_mfma_scale_f32_32x32x64_f8f6f4(p8, vf, o[d0], 0, 0, 0, 127, 0, 127); }
; }
; __device__ __forceinline__ void qkt9(f32x16& p0, f32x16& p1, const char* Kn, const char* Kr, const v8i32* qf, const float init, int r32, int hi) {
; #pragma unroll
;   for (int r = 0; r < 16; ++r) { p0[r] = init; p1[r] = init; }
; #pragma unroll
;   for (int s = 0; s < 2; ++s) { const int c0 = s * 4 + hi * 2;
;     const v8i32 a0 = cat8(*reinterpret_cast<const v4i32*>(Kn + KN8SW(r32, c0)), *reinterpret_cast<const v4i32*>(Kn + KN8SW(r32, c0 + 1)));
;     const v8i32 a1 = cat8(*reinterpret_cast<const v4i32*>(Kn + 4096 + KN8SW(r32, c0)), *reinterpret_cast<const v4i32*>(Kn + 4096 + KN8SW(r32, c0 + 1)));
;     p0 = __builtin_amdgcn_mfma_scale_f32_32x32x64_f8f6f4(a0, qf[s], p0, 0, 0, 0, 127, 0, 124);
;     p1 = __builtin_amdgcn_mfma_scale_f32_32x32x64_f8f6f4(a1, qf[s], p1, 0, 0, 0, 127, 0, 124); }
;   { const int c0 = hi * 2;
.Lmla_s0_cont:
	ds_read_b128 v[82:85], v166 offset:16384
	ds_read_b128 v[86:89], v167 offset:16384
	ds_read_b128 v[222:225], v166 offset:20480
	ds_read_b128 v[226:229], v167 offset:20480
	v_exp_f32_e32 v0, v114
	v_exp_f32_e32 v177, v115
	v_exp_f32_e32 v179, v116
	v_exp_f32_e32 v254, v117
	v_add_f32_e32 v219, v0, v177
	v_cvt_pk_fp8_f32 v246, v0, v177
	v_add_f32_e32 v219, v179, v219
	v_add_f32_e32 v219, v254, v219
	v_cvt_pk_fp8_f32 v246, v179, v254 op_sel:[0,0,1]
	s_waitcnt lgkmcnt(2)
	v_mfma_scale_f32_32x32x64_f8f6f4 v[82:97], v[82:89], v[146:153], v[230:245], v194, v193 op_sel_hi:[0,0,0]
	v_exp_f32_e32 v0, v118
	v_exp_f32_e32 v177, v119
	v_exp_f32_e32 v179, v120
	v_exp_f32_e32 v254, v121
	v_add_f32_e32 v219, v0, v219
	v_add_f32_e32 v219, v177, v219
	v_cvt_pk_fp8_f32 v247, v0, v177
	v_add_f32_e32 v219, v179, v219
	v_add_f32_e32 v219, v254, v219
	v_cvt_pk_fp8_f32 v247, v179, v254 op_sel:[0,0,1]
	ds_read_b128 v[114:117], v168 offset:16384
	ds_read_b128 v[118:121], v169 offset:16384
	s_waitcnt lgkmcnt(2)
	v_mfma_scale_f32_32x32x64_f8f6f4 v[66:81], v[222:229], v[146:153], v[230:245], v194, v193 op_sel_hi:[0,0,0]
	ds_read_b128 v[222:225], v168 offset:20480
	ds_read_b128 v[226:229], v169 offset:20480
	v_exp_f32_e32 v0, v122
	v_exp_f32_e32 v177, v123
	v_exp_f32_e32 v179, v124
	v_exp_f32_e32 v254, v125
	v_add_f32_e32 v219, v0, v219
	v_add_f32_e32 v219, v177, v219
	v_cvt_pk_fp8_f32 v248, v0, v177
	v_add_f32_e32 v219, v179, v219
	v_add_f32_e32 v219, v254, v219
	v_cvt_pk_fp8_f32 v248, v179, v254 op_sel:[0,0,1]
	v_exp_f32_e32 v0, v126
	v_exp_f32_e32 v177, v127
	v_exp_f32_e32 v179, v128
	v_exp_f32_e32 v254, v129
	v_add_f32_e32 v219, v0, v219
	v_add_f32_e32 v219, v177, v219
	v_cvt_pk_fp8_f32 v249, v0, v177
	v_add_f32_e32 v219, v179, v219
	v_add_f32_e32 v219, v254, v219
	v_cvt_pk_fp8_f32 v249, v179, v254 op_sel:[0,0,1]
	ds_read_b128 v[122:125], v170 offset:32768
	ds_read_b128 v[126:129], v171 offset:32768
	s_waitcnt vmcnt(0)
	ds_write_b128 v172, v[158:161] offset:8192
	ds_write_b128 v173, v[162:165] offset:24576
	s_waitcnt lgkmcnt(6)
	v_mfma_scale_f32_32x32x64_f8f6f4 v[82:97], v[114:121], v[138:145], v[82:97], v194, v193 op_sel_hi:[0,0,0]
	s_waitcnt lgkmcnt(0)
	s_barrier
	global_load_dwordx4 v[158:161], v176, s[18:19]
	global_load_dwordx4 v[162:165], v178, s[16:17]
	v_add_u32_e32 v176, 0x2000, v176
	v_add_u32_e32 v178, 0x20000, v178
	v_exp_f32_e32 v0, v98
	v_exp_f32_e32 v177, v99
	v_exp_f32_e32 v179, v100
	v_exp_f32_e32 v254, v101
	v_add_f32_e32 v219, v0, v219
	v_add_f32_e32 v219, v177, v219
	v_cvt_pk_fp8_f32 v250, v0, v177
	v_add_f32_e32 v219, v179, v219
	v_add_f32_e32 v219, v254, v219
	v_cvt_pk_fp8_f32 v250, v179, v254 op_sel:[0,0,1]
	s_waitcnt lgkmcnt(2)
	v_mfma_scale_f32_32x32x64_f8f6f4 v[66:81], v[222:229], v[138:145], v[66:81], v194, v193 op_sel_hi:[0,0,0]
	ds_read_b128 v[222:225], v170 offset:34816
	ds_read_b128 v[226:229], v171 offset:34816
	v_exp_f32_e32 v0, v102
	v_exp_f32_e32 v177, v103
	v_exp_f32_e32 v179, v104
	v_exp_f32_e32 v254, v105
	v_add_f32_e32 v219, v0, v219
	v_add_f32_e32 v219, v177, v219
	v_cvt_pk_fp8_f32 v251, v0, v177
	v_add_f32_e32 v219, v179, v219
	v_add_f32_e32 v219, v254, v219
	v_cvt_pk_fp8_f32 v251, v179, v254 op_sel:[0,0,1]
	v_exp_f32_e32 v0, v106
	v_exp_f32_e32 v177, v107
	v_exp_f32_e32 v179, v108
	v_exp_f32_e32 v254, v109
	v_add_f32_e32 v219, v0, v219
	v_add_f32_e32 v219, v177, v219
	v_cvt_pk_fp8_f32 v252, v0, v177
	v_add_f32_e32 v219, v179, v219
	v_add_f32_e32 v219, v254, v219
	v_cvt_pk_fp8_f32 v252, v179, v254 op_sel:[0,0,1]
	s_waitcnt lgkmcnt(2)
	v_mfma_scale_f32_32x32x64_f8f6f4 v[82:97], v[122:129], v[130:137], v[82:97], v194, v193 op_sel_hi:[0,0,0]
	v_exp_f32_e32 v0, v110
	v_exp_f32_e32 v177, v111
	v_exp_f32_e32 v179, v112
	v_exp_f32_e32 v254, v113
	v_add_f32_e32 v219, v0, v219
	v_add_f32_e32 v219, v177, v219
	v_cvt_pk_fp8_f32 v253, v0, v177
	v_add_f32_e32 v219, v179, v219
	v_add_f32_e32 v219, v254, v219
	v_cvt_pk_fp8_f32 v253, v179, v254 op_sel:[0,0,1]
	ds_read_b128 v[122:125], v185 offset:8192
	ds_read_b128 v[126:129], v186 offset:8192
	ds_read_b128 v[114:117], v185 offset:10240
	ds_read_b128 v[118:121], v186 offset:10240
	ds_read_b128 v[106:109], v185 offset:12288
	ds_read_b128 v[110:113], v186 offset:12288
	ds_read_b128 v[98:101], v185 offset:14336
	ds_read_b128 v[102:105], v186 offset:14336
	s_waitcnt lgkmcnt(8)
	v_mfma_scale_f32_32x32x64_f8f6f4 v[66:81], v[222:229], v[130:137], v[66:81], v194, v193 op_sel_hi:[0,0,0]
	v_mov_b32_e32 v0, v219
	s_nop 1
	v_permlane32_swap_b32_e32 v219, v0
	v_add_f32_e32 v219, v219, v0
	v_fma_f32 v209, v209, v221, v219
	v_max_f32_e32 v177, v82, v83
	v_max3_f32 v177, v177, v84, v85
	v_max3_f32 v177, v177, v86, v87
	v_max3_f32 v177, v177, v88, v89
	v_max3_f32 v177, v177, v90, v91
	v_max3_f32 v177, v177, v92, v93
	v_max3_f32 v177, v177, v94, v95
	v_max3_f32 v177, v177, v96, v97
	s_waitcnt lgkmcnt(6)
	v_mfma_scale_f32_32x32x64_f8f6f4 v[50:65], v[246:253], v[122:129], v[50:65], v194, v194 op_sel_hi:[0,0,0]
	s_waitcnt lgkmcnt(4)
	v_mfma_scale_f32_32x32x64_f8f6f4 v[34:49], v[246:253], v[114:121], v[34:49], v194, v194 op_sel_hi:[0,0,0]
	s_waitcnt lgkmcnt(2)
	v_mfma_scale_f32_32x32x64_f8f6f4 v[18:33], v[246:253], v[106:113], v[18:33], v194, v194 op_sel_hi:[0,0,0]
	s_waitcnt lgkmcnt(0)
	v_mfma_scale_f32_32x32x64_f8f6f4 v[2:17], v[246:253], v[98:105], v[2:17], v194, v194 op_sel_hi:[0,0,0]
	v_max_f32_e32 v0, v66, v67
	v_max3_f32 v0, v0, v68, v69
	v_max3_f32 v0, v0, v70, v71
	v_max3_f32 v0, v0, v72, v73
	v_max3_f32 v0, v0, v74, v75
	v_max3_f32 v0, v0, v76, v77
	v_max3_f32 v0, v0, v78, v79
	v_max3_f32 v0, v0, v80, v81
	v_max_f32_e32 v177, v177, v0
	v_mov_b32_e32 v0, v177
	v_mov_b32_e32 v218, 1.0
	s_nop 0
	v_permlane32_swap_b32_e32 v177, v0
	v_max_f32_e32 v177, v177, v0
	v_cmp_ge_f32_e32 vcc, s90, v177
	s_cmp_eq_u64 vcc, exec
	s_cbranch_scc0 .Lmla_s1_newmax
; __device__ __forceinline__ void finishSM9(f32x16& p0, f32x16& p1, float alpha, float& l_reg, v8i32& p8) {
; #pragma unroll
;   for (int r = 0; r < 16; ++r) { p0[r] = __builtin_amdgcn_exp2f(p0[r]); p1[r] = __builtin_amdgcn_exp2f(p1[r]); }
;   float ps = 0;
; #pragma unroll
;   for (int r = 0; r < 16; ++r) ps += p0[r];
; #pragma unroll
;   for (int r = 0; r < 16; ++r) ps += p1[r];
;   { auto rr = __builtin_amdgcn_permlane32_swap(__float_as_uint(ps), __float_as_uint(ps), false, false);
;     ps = __uint_as_float(rr[0]) + __uint_as_float(rr[1]); }
;   l_reg = l_reg * alpha + ps;
; #pragma unroll
;   for (int g = 0; g < 4; ++g) {
;     int w = __builtin_amdgcn_cvt_pk_fp8_f32(p0[4 * g], p0[4 * g + 1], 0, false); p8[g] = __builtin_amdgcn_cvt_pk_fp8_f32(p0[4 * g + 2], p0[4 * g + 3], w, true);
;     int u = __builtin_amdgcn_cvt_pk_fp8_f32(p1[4 * g], p1[4 * g + 1], 0, false); p8[4 + g] = __builtin_amdgcn_cvt_pk_fp8_f32(p1[4 * g + 2], p1[4 * g + 3], u, true); }
; }
; __device__ __forceinline__ void pv8(f32x16* o, const char* Vt, const v8i32 p8, int r32, int hi) {
;   const int sw = (r32 >> 2) & 3, a0 = r32 * 64 + (((hi * 2) ^ sw) << 4), a1 = r32 * 64 + (((hi * 2 + 1) ^ sw) << 4);
; #pragma unroll
;   for (int d0 = 0; d0 < 4; ++d0) {
;     const v8i32 vf = cat8(*reinterpret_cast<const v4i32*>(Vt + d0 * 2048 + a0), *reinterpret_cast<const v4i32*>(Vt + d0 * 2048 + a1));
;     o[d0] = __builtin_amdgcn_mfma_scale_f32_32x32x64_f8f6f4(p8, vf, o[d0], 0, 0, 0, 127, 0, 127); }
; }
; __device__ __forceinline__ void qkt9(f32x16& p0, f32x16& p1, const char* Kn, const char* Kr, const v8i32* qf, const float init, int r32, int hi) {
; #pragma unroll
;   for (int r = 0; r < 16; ++r) { p0[r] = init; p1[r] = init; }
; #pragma unroll
;   for (int s = 0; s < 2; ++s) { const int c0 = s * 4 + hi * 2;
;     const v8i32 a0 = cat8(*reinterpret_cast<const v4i32*>(Kn + KN8SW(r32, c0)), *reinterpret_cast<const v4i32*>(Kn + KN8SW(r32, c0 + 1)));
;     const v8i32 a1 = cat8(*reinterpret_cast<const v4i32*>(Kn + 4096 + KN8SW(r32, c0)), *reinterpret_cast<const v4i32*>(Kn + 4096 + KN8SW(r32, c0 + 1)));
;     p0 = __builtin_amdgcn_mfma_scale_f32_32x32x64_f8f6f4(a0, qf[s], p0, 0, 0, 0, 127, 0, 124);
;     p1 = __builtin_amdgcn_mfma_scale_f32_32x32x64_f8f6f4(a1, qf[s], p1, 0, 0, 0, 127, 0, 124); }
;   { const int c0 = hi * 2;
.Lmla_s1_cont:
	ds_read_b128 v[114:117], v166 offset:24576
	ds_read_b128 v[118:121], v167 offset:24576
	ds_read_b128 v[222:225], v166 offset:28672
	ds_read_b128 v[226:229], v167 offset:28672
	v_exp_f32_e32 v0, v82
	v_exp_f32_e32 v177, v83
	v_exp_f32_e32 v179, v84
	v_exp_f32_e32 v254, v85
	v_add_f32_e32 v219, v0, v177
	v_cvt_pk_fp8_f32 v246, v0, v177
	v_add_f32_e32 v219, v179, v219
	v_add_f32_e32 v219, v254, v219
	v_cvt_pk_fp8_f32 v246, v179, v254 op_sel:[0,0,1]
	s_waitcnt lgkmcnt(2)
	v_mfma_scale_f32_32x32x64_f8f6f4 v[114:129], v[114:121], v[146:153], v[230:245], v194, v193 op_sel_hi:[0,0,0]
	v_exp_f32_e32 v0, v86
	v_exp_f32_e32 v177, v87
	v_exp_f32_e32 v179, v88
	v_exp_f32_e32 v254, v89
	v_add_f32_e32 v219, v0, v219
	v_add_f32_e32 v219, v177, v219
	v_cvt_pk_fp8_f32 v247, v0, v177
	v_add_f32_e32 v219, v179, v219
	v_add_f32_e32 v219, v254, v219
	v_cvt_pk_fp8_f32 v247, v179, v254 op_sel:[0,0,1]
	ds_read_b128 v[82:85], v168 offset:24576
	ds_read_b128 v[86:89], v169 offset:24576
	s_waitcnt lgkmcnt(2)
	v_mfma_scale_f32_32x32x64_f8f6f4 v[98:113], v[222:229], v[146:153], v[230:245], v194, v193 op_sel_hi:[0,0,0]
	ds_read_b128 v[222:225], v168 offset:28672
	ds_read_b128 v[226:229], v169 offset:28672
	v_exp_f32_e32 v0, v90
	v_exp_f32_e32 v177, v91
	v_exp_f32_e32 v179, v92
	v_exp_f32_e32 v254, v93
	v_add_f32_e32 v219, v0, v219
	v_add_f32_e32 v219, v177, v219
	v_cvt_pk_fp8_f32 v248, v0, v177
	v_add_f32_e32 v219, v179, v219
	v_add_f32_e32 v219, v254, v219
	v_cvt_pk_fp8_f32 v248, v179, v254 op_sel:[0,0,1]
	v_exp_f32_e32 v0, v94
	v_exp_f32_e32 v177, v95
	v_exp_f32_e32 v179, v96
	v_exp_f32_e32 v254, v97
	v_add_f32_e32 v219, v0, v219
	v_add_f32_e32 v219, v177, v219
	v_cvt_pk_fp8_f32 v249, v0, v177
	v_add_f32_e32 v219, v179, v219
	v_add_f32_e32 v219, v254, v219
	v_cvt_pk_fp8_f32 v249, v179, v254 op_sel:[0,0,1]
	ds_read_b128 v[90:93], v170 offset:36864
	ds_read_b128 v[94:97], v171 offset:36864
	s_waitcnt vmcnt(0)
	ds_write_b128 v210, v[158:161]
	ds_write_b128 v211, v[162:165] offset:16384
	s_waitcnt lgkmcnt(6)
	v_mfma_scale_f32_32x32x64_f8f6f4 v[114:129], v[82:89], v[138:145], v[114:129], v194, v193 op_sel_hi:[0,0,0]
	s_waitcnt lgkmcnt(0)
	s_barrier
	global_load_dwordx4 v[158:161], v176, s[18:19]
	global_load_dwordx4 v[162:165], v178, s[16:17]
	v_add_u32_e32 v176, 0x2000, v176
	v_add_u32_e32 v178, 0x20000, v178
	v_exp_f32_e32 v0, v66
	v_exp_f32_e32 v177, v67
	v_exp_f32_e32 v179, v68
	v_exp_f32_e32 v254, v69
	v_add_f32_e32 v219, v0, v219
	v_add_f32_e32 v219, v177, v219
	v_cvt_pk_fp8_f32 v250, v0, v177
	v_add_f32_e32 v219, v179, v219
	v_add_f32_e32 v219, v254, v219
	v_cvt_pk_fp8_f32 v250, v179, v254 op_sel:[0,0,1]
	s_waitcnt lgkmcnt(2)
	v_mfma_scale_f32_32x32x64_f8f6f4 v[98:113], v[222:229], v[138:145], v[98:113], v194, v193 op_sel_hi:[0,0,0]
	ds_read_b128 v[222:225], v170 offset:38912
	ds_read_b128 v[226:229], v171 offset:38912
	v_exp_f32_e32 v0, v70
	v_exp_f32_e32 v177, v71
	v_exp_f32_e32 v179, v72
	v_exp_f32_e32 v254, v73
	v_add_f32_e32 v219, v0, v219
	v_add_f32_e32 v219, v177, v219
	v_cvt_pk_fp8_f32 v251, v0, v177
	v_add_f32_e32 v219, v179, v219
	v_add_f32_e32 v219, v254, v219
	v_cvt_pk_fp8_f32 v251, v179, v254 op_sel:[0,0,1]
	v_exp_f32_e32 v0, v74
	v_exp_f32_e32 v177, v75
	v_exp_f32_e32 v179, v76
	v_exp_f32_e32 v254, v77
	v_add_f32_e32 v219, v0, v219
	v_add_f32_e32 v219, v177, v219
	v_cvt_pk_fp8_f32 v252, v0, v177
	v_add_f32_e32 v219, v179, v219
	v_add_f32_e32 v219, v254, v219
	v_cvt_pk_fp8_f32 v252, v179, v254 op_sel:[0,0,1]
	s_waitcnt lgkmcnt(2)
	v_mfma_scale_f32_32x32x64_f8f6f4 v[114:129], v[90:97], v[130:137], v[114:129], v194, v193 op_sel_hi:[0,0,0]
	v_exp_f32_e32 v0, v78
	v_exp_f32_e32 v177, v79
	v_exp_f32_e32 v179, v80
	v_exp_f32_e32 v254, v81
	v_add_f32_e32 v219, v0, v219
	v_add_f32_e32 v219, v177, v219
	v_cvt_pk_fp8_f32 v253, v0, v177
	v_add_f32_e32 v219, v179, v219
	v_add_f32_e32 v219, v254, v219
	v_cvt_pk_fp8_f32 v253, v179, v254 op_sel:[0,0,1]
	ds_read_b128 v[90:93], v170 offset:0
	ds_read_b128 v[94:97], v171 offset:0
	ds_read_b128 v[82:85], v170 offset:2048
	ds_read_b128 v[86:89], v171 offset:2048
	ds_read_b128 v[74:77], v170 offset:4096
	ds_read_b128 v[78:81], v171 offset:4096
	ds_read_b128 v[66:69], v170 offset:6144
	ds_read_b128 v[70:73], v171 offset:6144
	s_waitcnt lgkmcnt(8)
	v_mfma_scale_f32_32x32x64_f8f6f4 v[98:113], v[222:229], v[130:137], v[98:113], v194, v193 op_sel_hi:[0,0,0]
	v_mov_b32_e32 v0, v219
	s_nop 1
	v_permlane32_swap_b32_e32 v219, v0
	v_add_f32_e32 v219, v219, v0
	v_fma_f32 v209, v209, v218, v219
	v_max_f32_e32 v177, v114, v115
	v_max3_f32 v177, v177, v116, v117
	v_max3_f32 v177, v177, v118, v119
	v_max3_f32 v177, v177, v120, v121
	v_max3_f32 v177, v177, v122, v123
	v_max3_f32 v177, v177, v124, v125
	v_max3_f32 v177, v177, v126, v127
	v_max3_f32 v177, v177, v128, v129
	s_waitcnt lgkmcnt(6)
	v_mfma_scale_f32_32x32x64_f8f6f4 v[50:65], v[246:253], v[90:97], v[50:65], v194, v194 op_sel_hi:[0,0,0]
	s_waitcnt lgkmcnt(4)
	v_mfma_scale_f32_32x32x64_f8f6f4 v[34:49], v[246:253], v[82:89], v[34:49], v194, v194 op_sel_hi:[0,0,0]
	s_waitcnt lgkmcnt(2)
	v_mfma_scale_f32_32x32x64_f8f6f4 v[18:33], v[246:253], v[74:81], v[18:33], v194, v194 op_sel_hi:[0,0,0]
	s_waitcnt lgkmcnt(0)
	v_mfma_scale_f32_32x32x64_f8f6f4 v[2:17], v[246:253], v[66:73], v[2:17], v194, v194 op_sel_hi:[0,0,0]
	v_max_f32_e32 v0, v98, v99
	v_max3_f32 v0, v0, v100, v101
	v_max3_f32 v0, v0, v102, v103
	v_max3_f32 v0, v0, v104, v105
	v_max3_f32 v0, v0, v106, v107
	v_max3_f32 v0, v0, v108, v109
	v_max3_f32 v0, v0, v110, v111
	v_max3_f32 v0, v0, v112, v113
	v_max_f32_e32 v177, v177, v0
	v_mov_b32_e32 v0, v177
	v_mov_b32_e32 v221, 1.0
	s_nop 0
	v_permlane32_swap_b32_e32 v177, v0
	v_max_f32_e32 v177, v177, v0
	v_cmp_ge_f32_e32 vcc, s90, v177
	s_cmp_eq_u64 vcc, exec
	s_cbranch_scc0 .Lmla_s2_newmax
; __device__ __forceinline__ void finishSM9(f32x16& p0, f32x16& p1, float alpha, float& l_reg, v8i32& p8) {
; #pragma unroll
;   for (int r = 0; r < 16; ++r) { p0[r] = __builtin_amdgcn_exp2f(p0[r]); p1[r] = __builtin_amdgcn_exp2f(p1[r]); }
;   float ps = 0;
; #pragma unroll
;   for (int r = 0; r < 16; ++r) ps += p0[r];
; #pragma unroll
;   for (int r = 0; r < 16; ++r) ps += p1[r];
;   { auto rr = __builtin_amdgcn_permlane32_swap(__float_as_uint(ps), __float_as_uint(ps), false, false);
;     ps = __uint_as_float(rr[0]) + __uint_as_float(rr[1]); }
;   l_reg = l_reg * alpha + ps;
; #pragma unroll
;   for (int g = 0; g < 4; ++g) {
;     int w = __builtin_amdgcn_cvt_pk_fp8_f32(p0[4 * g], p0[4 * g + 1], 0, false); p8[g] = __builtin_amdgcn_cvt_pk_fp8_f32(p0[4 * g + 2], p0[4 * g + 3], w, true);
;     int u = __builtin_amdgcn_cvt_pk_fp8_f32(p1[4 * g], p1[4 * g + 1], 0, false); p8[4 + g] = __builtin_amdgcn_cvt_pk_fp8_f32(p1[4 * g + 2], p1[4 * g + 3], u, true); }
; }
; __device__ __forceinline__ void pv8(f32x16* o, const char* Vt, const v8i32 p8, int r32, int hi) {
;   const int sw = (r32 >> 2) & 3, a0 = r32 * 64 + (((hi * 2) ^ sw) << 4), a1 = r32 * 64 + (((hi * 2 + 1) ^ sw) << 4);
; #pragma unroll
;   for (int d0 = 0; d0 < 4; ++d0) {
;     const v8i32 vf = cat8(*reinterpret_cast<const v4i32*>(Vt + d0 * 2048 + a0), *reinterpret_cast<const v4i32*>(Vt + d0 * 2048 + a1));
;     o[d0] = __builtin_amdgcn_mfma_scale_f32_32x32x64_f8f6f4(p8, vf, o[d0], 0, 0, 0, 127, 0, 127); }
; }
; __device__ __forceinline__ void qkt9(f32x16& p0, f32x16& p1, const char* Kn, const char* Kr, const v8i32* qf, const float init, int r32, int hi) {
; #pragma unroll
;   for (int r = 0; r < 16; ++r) { p0[r] = init; p1[r] = init; }
; #pragma unroll
;   for (int s = 0; s < 2; ++s) { const int c0 = s * 4 + hi * 2;
;     const v8i32 a0 = cat8(*reinterpret_cast<const v4i32*>(Kn + KN8SW(r32, c0)), *reinterpret_cast<const v4i32*>(Kn + KN8SW(r32, c0 + 1)));
;     const v8i32 a1 = cat8(*reinterpret_cast<const v4i32*>(Kn + 4096 + KN8SW(r32, c0)), *reinterpret_cast<const v4i32*>(Kn + 4096 + KN8SW(r32, c0 + 1)));
;     p0 = __builtin_amdgcn_mfma_scale_f32_32x32x64_f8f6f4(a0, qf[s], p0, 0, 0, 0, 127, 0, 124);
;     p1 = __builtin_amdgcn_mfma_scale_f32_32x32x64_f8f6f4(a1, qf[s], p1, 0, 0, 0, 127, 0, 124); }
;   { const int c0 = hi * 2;
.Lmla_s2_cont:
	ds_read_b128 v[82:85], v215 offset:16384
	ds_read_b128 v[86:89], v216 offset:16384
	ds_read_b128 v[222:225], v215 offset:20480
	ds_read_b128 v[226:229], v216 offset:20480
	v_exp_f32_e32 v0, v114
	v_exp_f32_e32 v177, v115
	v_exp_f32_e32 v179, v116
	v_exp_f32_e32 v254, v117
	v_add_f32_e32 v219, v0, v177
	v_cvt_pk_fp8_f32 v246, v0, v177
	v_add_f32_e32 v219, v179, v219
	v_add_f32_e32 v219, v254, v219
	v_cvt_pk_fp8_f32 v246, v179, v254 op_sel:[0,0,1]
	s_waitcnt lgkmcnt(2)
	v_mfma_scale_f32_32x32x64_f8f6f4 v[82:97], v[82:89], v[146:153], v[230:245], v194, v193 op_sel_hi:[0,0,0]
	v_exp_f32_e32 v0, v118
	v_exp_f32_e32 v177, v119
	v_exp_f32_e32 v179, v120
	v_exp_f32_e32 v254, v121
	v_add_f32_e32 v219, v0, v219
	v_add_f32_e32 v219, v177, v219
	v_cvt_pk_fp8_f32 v247, v0, v177
	v_add_f32_e32 v219, v179, v219
	v_add_f32_e32 v219, v254, v219
	v_cvt_pk_fp8_f32 v247, v179, v254 op_sel:[0,0,1]
	ds_read_b128 v[114:117], v213 offset:16384
	ds_read_b128 v[118:121], v214 offset:16384
	s_waitcnt lgkmcnt(2)
	v_mfma_scale_f32_32x32x64_f8f6f4 v[66:81], v[222:229], v[146:153], v[230:245], v194, v193 op_sel_hi:[0,0,0]
	ds_read_b128 v[222:225], v213 offset:20480
	ds_read_b128 v[226:229], v214 offset:20480
	v_exp_f32_e32 v0, v122
	v_exp_f32_e32 v177, v123
	v_exp_f32_e32 v179, v124
	v_exp_f32_e32 v254, v125
	v_add_f32_e32 v219, v0, v219
	v_add_f32_e32 v219, v177, v219
	v_cvt_pk_fp8_f32 v248, v0, v177
	v_add_f32_e32 v219, v179, v219
	v_add_f32_e32 v219, v254, v219
	v_cvt_pk_fp8_f32 v248, v179, v254 op_sel:[0,0,1]
	v_exp_f32_e32 v0, v126
	v_exp_f32_e32 v177, v127
	v_exp_f32_e32 v179, v128
	v_exp_f32_e32 v254, v129
	v_add_f32_e32 v219, v0, v219
	v_add_f32_e32 v219, v177, v219
	v_cvt_pk_fp8_f32 v249, v0, v177
	v_add_f32_e32 v219, v179, v219
	v_add_f32_e32 v219, v254, v219
	v_cvt_pk_fp8_f32 v249, v179, v254 op_sel:[0,0,1]
	ds_read_b128 v[122:125], v185 offset:32768
	ds_read_b128 v[126:129], v186 offset:32768
	s_waitcnt vmcnt(0)
	ds_write_b128 v210, v[158:161] offset:8192
	ds_write_b128 v211, v[162:165] offset:24576
	s_waitcnt lgkmcnt(6)
	v_mfma_scale_f32_32x32x64_f8f6f4 v[82:97], v[114:121], v[138:145], v[82:97], v194, v193 op_sel_hi:[0,0,0]
	s_waitcnt lgkmcnt(0)
	s_barrier
	global_load_dwordx4 v[158:161], v176, s[18:19]
	global_load_dwordx4 v[162:165], v178, s[16:17]
	v_add_u32_e32 v176, 0x2000, v176
	v_add_u32_e32 v178, 0x20000, v178
	v_exp_f32_e32 v0, v98
	v_exp_f32_e32 v177, v99
	v_exp_f32_e32 v179, v100
	v_exp_f32_e32 v254, v101
	v_add_f32_e32 v219, v0, v219
	v_add_f32_e32 v219, v177, v219
	v_cvt_pk_fp8_f32 v250, v0, v177
	v_add_f32_e32 v219, v179, v219
	v_add_f32_e32 v219, v254, v219
	v_cvt_pk_fp8_f32 v250, v179, v254 op_sel:[0,0,1]
	s_waitcnt lgkmcnt(2)
	v_mfma_scale_f32_32x32x64_f8f6f4 v[66:81], v[222:229], v[138:145], v[66:81], v194, v193 op_sel_hi:[0,0,0]
	ds_read_b128 v[222:225], v185 offset:34816
	ds_read_b128 v[226:229], v186 offset:34816
	v_exp_f32_e32 v0, v102
	v_exp_f32_e32 v177, v103
	v_exp_f32_e32 v179, v104
	v_exp_f32_e32 v254, v105
	v_add_f32_e32 v219, v0, v219
	v_add_f32_e32 v219, v177, v219
	v_cvt_pk_fp8_f32 v251, v0, v177
	v_add_f32_e32 v219, v179, v219
	v_add_f32_e32 v219, v254, v219
	v_cvt_pk_fp8_f32 v251, v179, v254 op_sel:[0,0,1]
	v_exp_f32_e32 v0, v106
	v_exp_f32_e32 v177, v107
	v_exp_f32_e32 v179, v108
	v_exp_f32_e32 v254, v109
	v_add_f32_e32 v219, v0, v219
	v_add_f32_e32 v219, v177, v219
	v_cvt_pk_fp8_f32 v252, v0, v177
	v_add_f32_e32 v219, v179, v219
	v_add_f32_e32 v219, v254, v219
	v_cvt_pk_fp8_f32 v252, v179, v254 op_sel:[0,0,1]
	s_waitcnt lgkmcnt(2)
	v_mfma_scale_f32_32x32x64_f8f6f4 v[82:97], v[122:129], v[130:137], v[82:97], v194, v193 op_sel_hi:[0,0,0]
	v_exp_f32_e32 v0, v110
	v_exp_f32_e32 v177, v111
	v_exp_f32_e32 v179, v112
	v_exp_f32_e32 v254, v113
	v_add_f32_e32 v219, v0, v219
	v_add_f32_e32 v219, v177, v219
	v_cvt_pk_fp8_f32 v253, v0, v177
	v_add_f32_e32 v219, v179, v219
	v_add_f32_e32 v219, v254, v219
	v_cvt_pk_fp8_f32 v253, v179, v254 op_sel:[0,0,1]
	ds_read_b128 v[122:125], v170 offset:8192
	ds_read_b128 v[126:129], v171 offset:8192
	ds_read_b128 v[114:117], v170 offset:10240
	ds_read_b128 v[118:121], v171 offset:10240
	ds_read_b128 v[106:109], v170 offset:12288
	ds_read_b128 v[110:113], v171 offset:12288
	ds_read_b128 v[98:101], v170 offset:14336
	ds_read_b128 v[102:105], v171 offset:14336
	s_waitcnt lgkmcnt(8)
	v_mfma_scale_f32_32x32x64_f8f6f4 v[66:81], v[222:229], v[130:137], v[66:81], v194, v193 op_sel_hi:[0,0,0]
	v_mov_b32_e32 v0, v219
	s_nop 1
	v_permlane32_swap_b32_e32 v219, v0
	v_add_f32_e32 v219, v219, v0
	v_fma_f32 v209, v209, v221, v219
	v_max_f32_e32 v177, v82, v83
	v_max3_f32 v177, v177, v84, v85
	v_max3_f32 v177, v177, v86, v87
	v_max3_f32 v177, v177, v88, v89
	v_max3_f32 v177, v177, v90, v91
	v_max3_f32 v177, v177, v92, v93
	v_max3_f32 v177, v177, v94, v95
	v_max3_f32 v177, v177, v96, v97
	s_waitcnt lgkmcnt(6)
	v_mfma_scale_f32_32x32x64_f8f6f4 v[50:65], v[246:253], v[122:129], v[50:65], v194, v194 op_sel_hi:[0,0,0]
	s_waitcnt lgkmcnt(4)
	v_mfma_scale_f32_32x32x64_f8f6f4 v[34:49], v[246:253], v[114:121], v[34:49], v194, v194 op_sel_hi:[0,0,0]
	s_waitcnt lgkmcnt(2)
	v_mfma_scale_f32_32x32x64_f8f6f4 v[18:33], v[246:253], v[106:113], v[18:33], v194, v194 op_sel_hi:[0,0,0]
	s_waitcnt lgkmcnt(0)
	v_mfma_scale_f32_32x32x64_f8f6f4 v[2:17], v[246:253], v[98:105], v[2:17], v194, v194 op_sel_hi:[0,0,0]
	v_max_f32_e32 v0, v66, v67
	v_max3_f32 v0, v0, v68, v69
	v_max3_f32 v0, v0, v70, v71
	v_max3_f32 v0, v0, v72, v73
	v_max3_f32 v0, v0, v74, v75
	v_max3_f32 v0, v0, v76, v77
	v_max3_f32 v0, v0, v78, v79
	v_max3_f32 v0, v0, v80, v81
	v_max_f32_e32 v177, v177, v0
	v_mov_b32_e32 v0, v177
	v_mov_b32_e32 v218, 1.0
	s_nop 0
	v_permlane32_swap_b32_e32 v177, v0
	v_max_f32_e32 v177, v177, v0
	v_cmp_ge_f32_e32 vcc, s90, v177
	s_cmp_eq_u64 vcc, exec
	s_cbranch_scc0 .Lmla_s3_newmax
; __device__ __forceinline__ void finishSM9(f32x16& p0, f32x16& p1, float alpha, float& l_reg, v8i32& p8) {
; #pragma unroll
;   for (int r = 0; r < 16; ++r) { p0[r] = __builtin_amdgcn_exp2f(p0[r]); p1[r] = __builtin_amdgcn_exp2f(p1[r]); }
;   float ps = 0;
; #pragma unroll
;   for (int r = 0; r < 16; ++r) ps += p0[r];
; #pragma unroll
;   for (int r = 0; r < 16; ++r) ps += p1[r];
;   { auto rr = __builtin_amdgcn_permlane32_swap(__float_as_uint(ps), __float_as_uint(ps), false, false);
;     ps = __uint_as_float(rr[0]) + __uint_as_float(rr[1]); }
;   l_reg = l_reg * alpha + ps;
; #pragma unroll
;   for (int g = 0; g < 4; ++g) {
;     int w = __builtin_amdgcn_cvt_pk_fp8_f32(p0[4 * g], p0[4 * g + 1], 0, false); p8[g] = __builtin_amdgcn_cvt_pk_fp8_f32(p0[4 * g + 2], p0[4 * g + 3], w, true);
;     int u = __builtin_amdgcn_cvt_pk_fp8_f32(p1[4 * g], p1[4 * g + 1], 0, false); p8[4 + g] = __builtin_amdgcn_cvt_pk_fp8_f32(p1[4 * g + 2], p1[4 * g + 3], u, true); }
; }
; __device__ __forceinline__ void pv8(f32x16* o, const char* Vt, const v8i32 p8, int r32, int hi) {
;   const int sw = (r32 >> 2) & 3, a0 = r32 * 64 + (((hi * 2) ^ sw) << 4), a1 = r32 * 64 + (((hi * 2 + 1) ^ sw) << 4);
; #pragma unroll
;   for (int d0 = 0; d0 < 4; ++d0) {
;     const v8i32 vf = cat8(*reinterpret_cast<const v4i32*>(Vt + d0 * 2048 + a0), *reinterpret_cast<const v4i32*>(Vt + d0 * 2048 + a1));
;     o[d0] = __builtin_amdgcn_mfma_scale_f32_32x32x64_f8f6f4(p8, vf, o[d0], 0, 0, 0, 127, 0, 127); }
; }
; __device__ __forceinline__ void qkt9(f32x16& p0, f32x16& p1, const char* Kn, const char* Kr, const v8i32* qf, const float init, int r32, int hi) {
; #pragma unroll
;   for (int r = 0; r < 16; ++r) { p0[r] = init; p1[r] = init; }
; #pragma unroll
;   for (int s = 0; s < 2; ++s) { const int c0 = s * 4 + hi * 2;
;     const v8i32 a0 = cat8(*reinterpret_cast<const v4i32*>(Kn + KN8SW(r32, c0)), *reinterpret_cast<const v4i32*>(Kn + KN8SW(r32, c0 + 1)));
;     const v8i32 a1 = cat8(*reinterpret_cast<const v4i32*>(Kn + 4096 + KN8SW(r32, c0)), *reinterpret_cast<const v4i32*>(Kn + 4096 + KN8SW(r32, c0 + 1)));
;     p0 = __builtin_amdgcn_mfma_scale_f32_32x32x64_f8f6f4(a0, qf[s], p0, 0, 0, 0, 127, 0, 124);
;     p1 = __builtin_amdgcn_mfma_scale_f32_32x32x64_f8f6f4(a1, qf[s], p1, 0, 0, 0, 127, 0, 124); }
;   { const int c0 = hi * 2;
.Lmla_s3_cont:
	s_add_i32 s30, s30, 1
	s_cmpk_lt_u32 s30, 63
	s_cbranch_scc1 .Lmla_stag_loop
	ds_read_b128 v[114:117], v215 offset:24576
	ds_read_b128 v[118:121], v216 offset:24576
	ds_read_b128 v[222:225], v215 offset:28672
	ds_read_b128 v[226:229], v216 offset:28672
	v_exp_f32_e32 v0, v82
	v_exp_f32_e32 v177, v83
	v_exp_f32_e32 v179, v84
	v_exp_f32_e32 v254, v85
	v_add_f32_e32 v219, v0, v177
	v_cvt_pk_fp8_f32 v246, v0, v177
	v_add_f32_e32 v219, v179, v219
	v_add_f32_e32 v219, v254, v219
	v_cvt_pk_fp8_f32 v246, v179, v254 op_sel:[0,0,1]
	s_waitcnt lgkmcnt(2)
	v_mfma_scale_f32_32x32x64_f8f6f4 v[114:129], v[114:121], v[146:153], v[230:245], v194, v193 op_sel_hi:[0,0,0]
	v_exp_f32_e32 v0, v86
	v_exp_f32_e32 v177, v87
	v_exp_f32_e32 v179, v88
	v_exp_f32_e32 v254, v89
	v_add_f32_e32 v219, v0, v219
	v_add_f32_e32 v219, v177, v219
	v_cvt_pk_fp8_f32 v247, v0, v177
	v_add_f32_e32 v219, v179, v219
	v_add_f32_e32 v219, v254, v219
	v_cvt_pk_fp8_f32 v247, v179, v254 op_sel:[0,0,1]
	ds_read_b128 v[82:85], v213 offset:24576
	ds_read_b128 v[86:89], v214 offset:24576
	s_waitcnt lgkmcnt(2)
	v_mfma_scale_f32_32x32x64_f8f6f4 v[98:113], v[222:229], v[146:153], v[230:245], v194, v193 op_sel_hi:[0,0,0]
	ds_read_b128 v[222:225], v213 offset:28672
	ds_read_b128 v[226:229], v214 offset:28672
	v_exp_f32_e32 v0, v90
	v_exp_f32_e32 v177, v91
	v_exp_f32_e32 v179, v92
	v_exp_f32_e32 v254, v93
	v_add_f32_e32 v219, v0, v219
	v_add_f32_e32 v219, v177, v219
	v_cvt_pk_fp8_f32 v248, v0, v177
	v_add_f32_e32 v219, v179, v219
	v_add_f32_e32 v219, v254, v219
	v_cvt_pk_fp8_f32 v248, v179, v254 op_sel:[0,0,1]
	v_exp_f32_e32 v0, v94
	v_exp_f32_e32 v177, v95
	v_exp_f32_e32 v179, v96
	v_exp_f32_e32 v254, v97
	v_add_f32_e32 v219, v0, v219
	v_add_f32_e32 v219, v177, v219
	v_cvt_pk_fp8_f32 v249, v0, v177
	v_add_f32_e32 v219, v179, v219
	v_add_f32_e32 v219, v254, v219
	v_cvt_pk_fp8_f32 v249, v179, v254 op_sel:[0,0,1]
	ds_read_b128 v[90:93], v185 offset:36864
	ds_read_b128 v[94:97], v186 offset:36864
	s_waitcnt vmcnt(0)
	ds_write_b128 v172, v[158:161]
	ds_write_b128 v173, v[162:165] offset:16384
	s_waitcnt lgkmcnt(6)
	v_mfma_scale_f32_32x32x64_f8f6f4 v[114:129], v[82:89], v[138:145], v[114:129], v194, v193 op_sel_hi:[0,0,0]
	s_waitcnt lgkmcnt(0)
	s_barrier
	global_load_dwordx4 v[158:161], v176, s[18:19]
	global_load_dwordx4 v[162:165], v178, s[16:17]
	v_add_u32_e32 v176, 0x2000, v176
	v_add_u32_e32 v178, 0x20000, v178
	v_exp_f32_e32 v0, v66
	v_exp_f32_e32 v177, v67
	v_exp_f32_e32 v179, v68
	v_exp_f32_e32 v254, v69
	v_add_f32_e32 v219, v0, v219
	v_add_f32_e32 v219, v177, v219
	v_cvt_pk_fp8_f32 v250, v0, v177
	v_add_f32_e32 v219, v179, v219
	v_add_f32_e32 v219, v254, v219
	v_cvt_pk_fp8_f32 v250, v179, v254 op_sel:[0,0,1]
	s_waitcnt lgkmcnt(2)
	v_mfma_scale_f32_32x32x64_f8f6f4 v[98:113], v[222:229], v[138:145], v[98:113], v194, v193 op_sel_hi:[0,0,0]
	ds_read_b128 v[222:225], v185 offset:38912
	ds_read_b128 v[226:229], v186 offset:38912
	v_exp_f32_e32 v0, v70
	v_exp_f32_e32 v177, v71
	v_exp_f32_e32 v179, v72
	v_exp_f32_e32 v254, v73
	v_add_f32_e32 v219, v0, v219
	v_add_f32_e32 v219, v177, v219
	v_cvt_pk_fp8_f32 v251, v0, v177
	v_add_f32_e32 v219, v179, v219
	v_add_f32_e32 v219, v254, v219
	v_cvt_pk_fp8_f32 v251, v179, v254 op_sel:[0,0,1]
	v_exp_f32_e32 v0, v74
	v_exp_f32_e32 v177, v75
	v_exp_f32_e32 v179, v76
	v_exp_f32_e32 v254, v77
	v_add_f32_e32 v219, v0, v219
	v_add_f32_e32 v219, v177, v219
	v_cvt_pk_fp8_f32 v252, v0, v177
	v_add_f32_e32 v219, v179, v219
	v_add_f32_e32 v219, v254, v219
	v_cvt_pk_fp8_f32 v252, v179, v254 op_sel:[0,0,1]
	s_waitcnt lgkmcnt(2)
	v_mfma_scale_f32_32x32x64_f8f6f4 v[114:129], v[90:97], v[130:137], v[114:129], v194, v193 op_sel_hi:[0,0,0]
	v_exp_f32_e32 v0, v78
	v_exp_f32_e32 v177, v79
	v_exp_f32_e32 v179, v80
	v_exp_f32_e32 v254, v81
	v_add_f32_e32 v219, v0, v219
	v_add_f32_e32 v219, v177, v219
	v_cvt_pk_fp8_f32 v253, v0, v177
	v_add_f32_e32 v219, v179, v219
	v_add_f32_e32 v219, v254, v219
	v_cvt_pk_fp8_f32 v253, v179, v254 op_sel:[0,0,1]
	ds_read_b128 v[90:93], v185 offset:0
	ds_read_b128 v[94:97], v186 offset:0
	ds_read_b128 v[82:85], v185 offset:2048
	ds_read_b128 v[86:89], v186 offset:2048
	ds_read_b128 v[74:77], v185 offset:4096
	ds_read_b128 v[78:81], v186 offset:4096
	ds_read_b128 v[66:69], v185 offset:6144
	ds_read_b128 v[70:73], v186 offset:6144
	s_waitcnt lgkmcnt(8)
	v_mfma_scale_f32_32x32x64_f8f6f4 v[98:113], v[222:229], v[130:137], v[98:113], v194, v193 op_sel_hi:[0,0,0]
	v_mov_b32_e32 v0, v219
	s_nop 1
	v_permlane32_swap_b32_e32 v219, v0
	v_add_f32_e32 v219, v219, v0
	v_fma_f32 v209, v209, v218, v219
	v_max_f32_e32 v177, v114, v115
	v_max3_f32 v177, v177, v116, v117
	v_max3_f32 v177, v177, v118, v119
	v_max3_f32 v177, v177, v120, v121
	v_max3_f32 v177, v177, v122, v123
	v_max3_f32 v177, v177, v124, v125
	v_max3_f32 v177, v177, v126, v127
	v_max3_f32 v177, v177, v128, v129
	s_waitcnt lgkmcnt(6)
	v_mfma_scale_f32_32x32x64_f8f6f4 v[50:65], v[246:253], v[90:97], v[50:65], v194, v194 op_sel_hi:[0,0,0]
	s_waitcnt lgkmcnt(4)
	v_mfma_scale_f32_32x32x64_f8f6f4 v[34:49], v[246:253], v[82:89], v[34:49], v194, v194 op_sel_hi:[0,0,0]
	s_waitcnt lgkmcnt(2)
	v_mfma_scale_f32_32x32x64_f8f6f4 v[18:33], v[246:253], v[74:81], v[18:33], v194, v194 op_sel_hi:[0,0,0]
	s_waitcnt lgkmcnt(0)
	v_mfma_scale_f32_32x32x64_f8f6f4 v[2:17], v[246:253], v[66:73], v[2:17], v194, v194 op_sel_hi:[0,0,0]
	v_max_f32_e32 v0, v98, v99
	v_max3_f32 v0, v0, v100, v101
	v_max3_f32 v0, v0, v102, v103
	v_max3_f32 v0, v0, v104, v105
	v_max3_f32 v0, v0, v106, v107
	v_max3_f32 v0, v0, v108, v109
	v_max3_f32 v0, v0, v110, v111
	v_max3_f32 v0, v0, v112, v113
	v_max_f32_e32 v177, v177, v0
	v_mov_b32_e32 v0, v177
	v_mov_b32_e32 v221, 1.0
	s_nop 0
	v_permlane32_swap_b32_e32 v177, v0
	v_max_f32_e32 v177, v177, v0
	v_cmp_ge_f32_e32 vcc, s90, v177
	s_cmp_eq_u64 vcc, exec
	s_cbranch_scc0 .Lmla_q0_newmax
; __device__ __forceinline__ void finishSM9(f32x16& p0, f32x16& p1, float alpha, float& l_reg, v8i32& p8) {
; #pragma unroll
;   for (int r = 0; r < 16; ++r) { p0[r] = __builtin_amdgcn_exp2f(p0[r]); p1[r] = __builtin_amdgcn_exp2f(p1[r]); }
;   float ps = 0;
; #pragma unroll
;   for (int r = 0; r < 16; ++r) ps += p0[r];
; #pragma unroll
;   for (int r = 0; r < 16; ++r) ps += p1[r];
;   { auto rr = __builtin_amdgcn_permlane32_swap(__float_as_uint(ps), __float_as_uint(ps), false, false);
;     ps = __uint_as_float(rr[0]) + __uint_as_float(rr[1]); }
;   l_reg = l_reg * alpha + ps;
; #pragma unroll
;   for (int g = 0; g < 4; ++g) {
;     int w = __builtin_amdgcn_cvt_pk_fp8_f32(p0[4 * g], p0[4 * g + 1], 0, false); p8[g] = __builtin_amdgcn_cvt_pk_fp8_f32(p0[4 * g + 2], p0[4 * g + 3], w, true);
;     int u = __builtin_amdgcn_cvt_pk_fp8_f32(p1[4 * g], p1[4 * g + 1], 0, false); p8[4 + g] = __builtin_amdgcn_cvt_pk_fp8_f32(p1[4 * g + 2], p1[4 * g + 3], u, true); }
; }
; __device__ __forceinline__ void pv8(f32x16* o, const char* Vt, const v8i32 p8, int r32, int hi) {
;   const int sw = (r32 >> 2) & 3, a0 = r32 * 64 + (((hi * 2) ^ sw) << 4), a1 = r32 * 64 + (((hi * 2 + 1) ^ sw) << 4);
; #pragma unroll
;   for (int d0 = 0; d0 < 4; ++d0) {
;     const v8i32 vf = cat8(*reinterpret_cast<const v4i32*>(Vt + d0 * 2048 + a0), *reinterpret_cast<const v4i32*>(Vt + d0 * 2048 + a1));
;     o[d0] = __builtin_amdgcn_mfma_scale_f32_32x32x64_f8f6f4(p8, vf, o[d0], 0, 0, 0, 127, 0, 127); }
; }
; __device__ __forceinline__ void qkt9(f32x16& p0, f32x16& p1, const char* Kn, const char* Kr, const v8i32* qf, const float init, int r32, int hi) {
; #pragma unroll
;   for (int r = 0; r < 16; ++r) { p0[r] = init; p1[r] = init; }
; #pragma unroll
;   for (int s = 0; s < 2; ++s) { const int c0 = s * 4 + hi * 2;
;     const v8i32 a0 = cat8(*reinterpret_cast<const v4i32*>(Kn + KN8SW(r32, c0)), *reinterpret_cast<const v4i32*>(Kn + KN8SW(r32, c0 + 1)));
;     const v8i32 a1 = cat8(*reinterpret_cast<const v4i32*>(Kn + 4096 + KN8SW(r32, c0)), *reinterpret_cast<const v4i32*>(Kn + 4096 + KN8SW(r32, c0 + 1)));
;     p0 = __builtin_amdgcn_mfma_scale_f32_32x32x64_f8f6f4(a0, qf[s], p0, 0, 0, 0, 127, 0, 124);
;     p1 = __builtin_amdgcn_mfma_scale_f32_32x32x64_f8f6f4(a1, qf[s], p1, 0, 0, 0, 127, 0, 124); }
;   { const int c0 = hi * 2;
.Lmla_q0_cont:
	ds_read_b128 v[82:85], v166 offset:16384
	ds_read_b128 v[86:89], v167 offset:16384
	ds_read_b128 v[222:225], v166 offset:20480
	ds_read_b128 v[226:229], v167 offset:20480
	v_exp_f32_e32 v0, v114
	v_exp_f32_e32 v177, v115
	v_exp_f32_e32 v179, v116
	v_exp_f32_e32 v254, v117
	v_add_f32_e32 v219, v0, v177
	v_cvt_pk_fp8_f32 v246, v0, v177
	v_add_f32_e32 v219, v179, v219
	v_add_f32_e32 v219, v254, v219
	v_cvt_pk_fp8_f32 v246, v179, v254 op_sel:[0,0,1]
	s_waitcnt lgkmcnt(2)
	v_mfma_scale_f32_32x32x64_f8f6f4 v[82:97], v[82:89], v[146:153], v[230:245], v194, v193 op_sel_hi:[0,0,0]
	v_exp_f32_e32 v0, v118
	v_exp_f32_e32 v177, v119
	v_exp_f32_e32 v179, v120
	v_exp_f32_e32 v254, v121
	v_add_f32_e32 v219, v0, v219
	v_add_f32_e32 v219, v177, v219
	v_cvt_pk_fp8_f32 v247, v0, v177
	v_add_f32_e32 v219, v179, v219
	v_add_f32_e32 v219, v254, v219
	v_cvt_pk_fp8_f32 v247, v179, v254 op_sel:[0,0,1]
	ds_read_b128 v[114:117], v168 offset:16384
	ds_read_b128 v[118:121], v169 offset:16384
	s_waitcnt lgkmcnt(2)
	v_mfma_scale_f32_32x32x64_f8f6f4 v[66:81], v[222:229], v[146:153], v[230:245], v194, v193 op_sel_hi:[0,0,0]
	ds_read_b128 v[222:225], v168 offset:20480
	ds_read_b128 v[226:229], v169 offset:20480
	v_exp_f32_e32 v0, v122
	v_exp_f32_e32 v177, v123
	v_exp_f32_e32 v179, v124
	v_exp_f32_e32 v254, v125
	v_add_f32_e32 v219, v0, v219
	v_add_f32_e32 v219, v177, v219
	v_cvt_pk_fp8_f32 v248, v0, v177
	v_add_f32_e32 v219, v179, v219
	v_add_f32_e32 v219, v254, v219
	v_cvt_pk_fp8_f32 v248, v179, v254 op_sel:[0,0,1]
	v_exp_f32_e32 v0, v126
	v_exp_f32_e32 v177, v127
	v_exp_f32_e32 v179, v128
	v_exp_f32_e32 v254, v129
	v_add_f32_e32 v219, v0, v219
	v_add_f32_e32 v219, v177, v219
	v_cvt_pk_fp8_f32 v249, v0, v177
	v_add_f32_e32 v219, v179, v219
	v_add_f32_e32 v219, v254, v219
	v_cvt_pk_fp8_f32 v249, v179, v254 op_sel:[0,0,1]
	ds_read_b128 v[122:125], v170 offset:32768
	ds_read_b128 v[126:129], v171 offset:32768
	s_waitcnt vmcnt(0)
	ds_write_b128 v172, v[158:161] offset:8192
	ds_write_b128 v173, v[162:165] offset:24576
	s_waitcnt lgkmcnt(6)
	v_mfma_scale_f32_32x32x64_f8f6f4 v[82:97], v[114:121], v[138:145], v[82:97], v194, v193 op_sel_hi:[0,0,0]
	s_waitcnt lgkmcnt(0)
	s_barrier
	v_exp_f32_e32 v0, v98
	v_exp_f32_e32 v177, v99
	v_exp_f32_e32 v179, v100
	v_exp_f32_e32 v254, v101
	v_add_f32_e32 v219, v0, v219
	v_add_f32_e32 v219, v177, v219
	v_cvt_pk_fp8_f32 v250, v0, v177
	v_add_f32_e32 v219, v179, v219
	v_add_f32_e32 v219, v254, v219
	v_cvt_pk_fp8_f32 v250, v179, v254 op_sel:[0,0,1]
	s_waitcnt lgkmcnt(2)
	v_mfma_scale_f32_32x32x64_f8f6f4 v[66:81], v[222:229], v[138:145], v[66:81], v194, v193 op_sel_hi:[0,0,0]
	ds_read_b128 v[222:225], v170 offset:34816
	ds_read_b128 v[226:229], v171 offset:34816
	v_exp_f32_e32 v0, v102
	v_exp_f32_e32 v177, v103
	v_exp_f32_e32 v179, v104
	v_exp_f32_e32 v254, v105
	v_add_f32_e32 v219, v0, v219
	v_add_f32_e32 v219, v177, v219
	v_cvt_pk_fp8_f32 v251, v0, v177
	v_add_f32_e32 v219, v179, v219
	v_add_f32_e32 v219, v254, v219
	v_cvt_pk_fp8_f32 v251, v179, v254 op_sel:[0,0,1]
	v_exp_f32_e32 v0, v106
	v_exp_f32_e32 v177, v107
	v_exp_f32_e32 v179, v108
	v_exp_f32_e32 v254, v109
	v_add_f32_e32 v219, v0, v219
	v_add_f32_e32 v219, v177, v219
	v_cvt_pk_fp8_f32 v252, v0, v177
	v_add_f32_e32 v219, v179, v219
	v_add_f32_e32 v219, v254, v219
	v_cvt_pk_fp8_f32 v252, v179, v254 op_sel:[0,0,1]
	s_waitcnt lgkmcnt(2)
	v_mfma_scale_f32_32x32x64_f8f6f4 v[82:97], v[122:129], v[130:137], v[82:97], v194, v193 op_sel_hi:[0,0,0]
	v_exp_f32_e32 v0, v110
	v_exp_f32_e32 v177, v111
	v_exp_f32_e32 v179, v112
	v_exp_f32_e32 v254, v113
	v_add_f32_e32 v219, v0, v219
	v_add_f32_e32 v219, v177, v219
	v_cvt_pk_fp8_f32 v253, v0, v177
	v_add_f32_e32 v219, v179, v219
	v_add_f32_e32 v219, v254, v219
	v_cvt_pk_fp8_f32 v253, v179, v254 op_sel:[0,0,1]
	ds_read_b128 v[122:125], v185 offset:8192
	ds_read_b128 v[126:129], v186 offset:8192
	ds_read_b128 v[114:117], v185 offset:10240
	ds_read_b128 v[118:121], v186 offset:10240
	ds_read_b128 v[106:109], v185 offset:12288
	ds_read_b128 v[110:113], v186 offset:12288
	ds_read_b128 v[98:101], v185 offset:14336
	ds_read_b128 v[102:105], v186 offset:14336
	s_waitcnt lgkmcnt(8)
	v_mfma_scale_f32_32x32x64_f8f6f4 v[66:81], v[222:229], v[130:137], v[66:81], v194, v193 op_sel_hi:[0,0,0]
	v_mov_b32_e32 v0, v219
	s_nop 1
	v_permlane32_swap_b32_e32 v219, v0
	v_add_f32_e32 v219, v219, v0
	v_fma_f32 v209, v209, v221, v219
	v_max_f32_e32 v177, v82, v83
	v_max3_f32 v177, v177, v84, v85
	v_max3_f32 v177, v177, v86, v87
	v_max3_f32 v177, v177, v88, v89
	v_max3_f32 v177, v177, v90, v91
	v_max3_f32 v177, v177, v92, v93
	v_max3_f32 v177, v177, v94, v95
	v_max3_f32 v177, v177, v96, v97
	s_waitcnt lgkmcnt(6)
	v_mfma_scale_f32_32x32x64_f8f6f4 v[50:65], v[246:253], v[122:129], v[50:65], v194, v194 op_sel_hi:[0,0,0]
	s_waitcnt lgkmcnt(4)
	v_mfma_scale_f32_32x32x64_f8f6f4 v[34:49], v[246:253], v[114:121], v[34:49], v194, v194 op_sel_hi:[0,0,0]
	s_waitcnt lgkmcnt(2)
	v_mfma_scale_f32_32x32x64_f8f6f4 v[18:33], v[246:253], v[106:113], v[18:33], v194, v194 op_sel_hi:[0,0,0]
	s_waitcnt lgkmcnt(0)
	v_mfma_scale_f32_32x32x64_f8f6f4 v[2:17], v[246:253], v[98:105], v[2:17], v194, v194 op_sel_hi:[0,0,0]
	v_max_f32_e32 v0, v66, v67
	v_max3_f32 v0, v0, v68, v69
	v_max3_f32 v0, v0, v70, v71
	v_max3_f32 v0, v0, v72, v73
	v_max3_f32 v0, v0, v74, v75
	v_max3_f32 v0, v0, v76, v77
	v_max3_f32 v0, v0, v78, v79
	v_max3_f32 v0, v0, v80, v81
	v_max_f32_e32 v177, v177, v0
	v_mov_b32_e32 v0, v177
	v_mov_b32_e32 v218, 1.0
	s_nop 0
	v_permlane32_swap_b32_e32 v177, v0
	v_max_f32_e32 v177, v177, v0
	v_cmp_ge_f32_e32 vcc, s90, v177
	s_cmp_eq_u64 vcc, exec
	s_cbranch_scc0 .Lmla_q1_newmax
